# NSA sel/window loops: s_setprio toggles around MFMA groups removed (hazard distances re-padded), on top of barrier hop skip + bias-read hoist
# baseline (speedup 1.0000x reference)
; template <int MODE>
; __device__ __forceinline__ void nsa_compute(int cur, int buf, int t, int hl, u64 mymask, const bf16x8 (&Qf)[2][2], f32x4 (&O)[4][2], float (&m)[2], float (&l)[2],
;                                             const float (&inv)[2], float* impw, char* lds) {
;     ...
;   const int base = (MODE <= 1) ? (t - 31 - 16 * (cur * 64 + 4 * fq) + 64) : (t - cur * 64 - 4 * fq + 64);
; #pragma unroll
;   for (int s2 = 0; s2 < 2; ++s2) {
;     f32x4 S[2][2] = {};
;     bf16x8 kfr[2][2];
; #pragma unroll
;     for (int ks = 0; ks < 2; ++ks)
; #pragma unroll
;       for (int kk = 0; kk < 2; ++kk) kfr[ks][kk] = *(const bf16x8*)(kt + (32 * s2 + 16 * kk + fr) * 128 + (((ks * 4 + fq) ^ (fr & 7)) << 4));
;     __builtin_amdgcn_s_setprio(1);
; #pragma unroll
;     for (int ks = 0; ks < 2; ++ks)
; #pragma unroll
;       for (int kk = 0; kk < 2; ++kk)
; #pragma unroll
;         for (int r = 0; r < 2; ++r) S[kk][r] = mfma16(kfr[ks][kk], Qf[r][ks], S[kk][r]);
;     __builtin_amdgcn_s_setprio(0);
;     bf16x8 Pf[2];
;     float g1s[2] = {0.f, 0.f}, p3s[2] = {0.f, 0.f};
; #pragma unroll
;     for (int r = 0; r < 2; ++r) {
;       float sv[2][4];
; #pragma unroll
;       for (int kk = 0; kk < 2; ++kk)
; #pragma unroll
;         for (int e = 0; e < 4; ++e) {
;           const int off = 32 * s2 + 16 * kk + e;
;           int idx;
;           if (MODE <= 1) { idx = base - 16 * off; idx = idx > 0 ? idx : 0; } else idx = base - off;
;           sv[kk][e] = S[kk][r][e] * (0.125f * LOG2E) + tb[r * TS + idx];
;         }
;       float pv[2][4];
;       if (MODE == 1) {
; #pragma unroll
;         for (int kk = 0; kk < 2; ++kk)
; #pragma unroll
;           for (int e = 0; e < 4; ++e) pv[kk][e] = __builtin_amdgcn_exp2f(sv[kk][e] - m[r]) * inv[r];
; #pragma unroll
;         for (int kk = 0; kk < 2; ++kk) { g1s[kk] += pv[kk][0] + pv[kk][1] + pv[kk][2] + 0.5f * pv[kk][3]; p3s[kk] += 0.5f * pv[kk][3]; }
;       } else {
;         const float mxa = fmaxf(fmaxf(sv[0][0], sv[0][1]), sv[0][2]), mxb = fmaxf(fmaxf(sv[0][3], sv[1][0]), sv[1][1]);
;         float mx = fmaxf(fmaxf(fmaxf(sv[1][2], sv[1][3]), mxa), mxb);
;         if (MODE == 2) mx = selok ? mx : -__builtin_inff();
;         if (__any(mx > m[r] + 8.0f)) {
;           mx = fmaxf(mx, __shfl_xor(mx, 16)); mx = fmaxf(mx, __shfl_xor(mx, 32));
;           const float mn = fmaxf(m[r], mx), al = __builtin_amdgcn_exp2f(m[r] - mn);
.LBB0_361:
	v_mov_b32 v72, v179
	s_lshl_b32 s64, s46, 13
	v_lshrrev_b32_e32 v73, 4, v72
	v_bfe_u32 v80, v72, 4, 2
	v_and_b32_e32 v81, 7, v72
	v_and_b32_e32 v92, 15, v72
	v_lshlrev_b32_e32 v93, 2, v80
	v_bitop3_b32 v72, v73, v81, 3 bitop3:0x6c
	v_bitop3_b32 v80, v80, v81, 4 bitop3:0x36
	v_lshlrev_b32_e32 v90, 7, v92
	v_lshl_or_b32 v91, v72, 4, s64
	v_lshl_or_b32 v100, v80, 4, s64
	v_or_b32_e32 v76, v91, v90
	v_or_b32_e32 v84, v100, v90
	ds_read_b128 v[72:75], v76
	ds_read_b128 v[76:79], v76 offset:2048
	ds_read_b128 v[80:83], v84
	ds_read_b128 v[84:87], v84 offset:2048
	s_mov_b32 s17, s74
	s_mov_b32 s74, s73
	v_sub_u32_e32 v251, v180, v93
	v_lshl_add_u32 v251, v251, 2, v235
	s_lshl_b32 s17, s17, 8
	v_subrev_u32_e32 v250, s17, v251
	v_add_u32_e32 v249, 0xa00, v250
	ds_read2_b32 v[98:99], v250 offset0:63 offset1:64
	ds_read2_b32 v[102:103], v250 offset0:61 offset1:62
	ds_read2_b32 v[168:169], v250 offset0:47 offset1:48
	ds_read2_b32 v[170:171], v250 offset0:45 offset1:46
	ds_read2_b32 v[172:173], v249 offset0:63 offset1:64
	ds_read2_b32 v[174:175], v249 offset0:61 offset1:62
	ds_read2_b32 v[194:195], v249 offset0:47 offset1:48
	ds_read2_b32 v[198:199], v249 offset0:45 offset1:46
	s_waitcnt lgkmcnt(11)
	v_mfma_f32_16x16x32_bf16 v[94:97], v[72:75], v[0:3], 0
	v_mfma_f32_16x16x32_bf16 v[72:75], v[72:75], v[8:11], 0
	s_waitcnt lgkmcnt(10)
	v_mfma_f32_16x16x32_bf16 v[140:143], v[76:79], v[8:11], 0
	v_mfma_f32_16x16x32_bf16 v[136:139], v[76:79], v[0:3], 0
	s_waitcnt lgkmcnt(9)
	v_mfma_f32_16x16x32_bf16 v[94:97], v[80:83], v[4:7], v[94:97]
	v_mfma_f32_16x16x32_bf16 v[76:79], v[80:83], v[12:15], v[72:75]
	s_waitcnt lgkmcnt(8)
	v_mfma_f32_16x16x32_bf16 v[72:75], v[84:87], v[12:15], v[140:143]
	v_mfma_f32_16x16x32_bf16 v[144:147], v[84:87], v[4:7], v[136:139]
	v_sub_u32_e32 v80, v180, v93
	v_lshl_add_u32 v80, v80, 2, v235
	s_nop 0
	v_subrev_u32_e32 v136, s17, v80
	s_waitcnt lgkmcnt(7)
	v_fmamk_f32 v94, v94, 0x3e38aa3b, v99
	v_fmamk_f32 v86, v95, 0x3e38aa3b, v98
	s_waitcnt lgkmcnt(6)
	v_fmamk_f32 v87, v96, 0x3e38aa3b, v103
	v_fmamk_f32 v84, v97, 0x3e38aa3b, v102
	s_waitcnt lgkmcnt(5)
	v_fmamk_f32 v81, v144, 0x3e38aa3b, v169
	v_fmamk_f32 v80, v145, 0x3e38aa3b, v168
	s_waitcnt lgkmcnt(4)
	v_fmamk_f32 v83, v146, 0x3e38aa3b, v171
	v_fmamk_f32 v82, v147, 0x3e38aa3b, v170
	v_max3_f32 v85, v94, v86, v87
	v_max3_f32 v88, v84, v81, v80
	v_max_f32_e32 v89, v83, v82
	v_max3_f32 v85, v89, v85, v88
	v_add_f32_e32 v88, 0x41000000, v192
	v_cmp_gt_f32_e32 vcc, v85, v88
	s_cbranch_vccz .LBB0_363
	ds_bpermute_b32 v88, v233, v85
	v_max_f32_e32 v85, v85, v85
	v_mov_b32_e32 v89, v193
	s_waitcnt lgkmcnt(0)
	v_max_f32_e32 v88, v88, v88
	v_max_f32_e32 v85, v85, v88
	ds_bpermute_b32 v88, v234, v85
	s_waitcnt lgkmcnt(0)
	v_max3_f32 v88, v192, v85, v88
	v_sub_f32_e32 v85, v192, v88
	v_exp_f32_e32 v96, v85
	v_mov_b64_e32 v[192:193], v[88:89]
	v_mul_f32_e32 v190, v190, v96
	v_pk_mul_f32 v[118:119], v[118:119], v[96:97] op_sel_hi:[1,0]
	v_pk_mul_f32 v[116:117], v[116:117], v[96:97] op_sel_hi:[1,0]
	v_pk_mul_f32 v[126:127], v[126:127], v[96:97] op_sel_hi:[1,0]
	v_pk_mul_f32 v[124:125], v[124:125], v[96:97] op_sel_hi:[1,0]
	v_pk_mul_f32 v[130:131], v[130:131], v[96:97] op_sel_hi:[1,0]
	v_pk_mul_f32 v[128:129], v[128:129], v[96:97] op_sel_hi:[1,0]
	v_pk_mul_f32 v[134:135], v[134:135], v[96:97] op_sel_hi:[1,0]
	v_pk_mul_f32 v[132:133], v[132:133], v[96:97] op_sel_hi:[1,0]
	s_branch .LBB0_364

; template <int MODE>
; __device__ __forceinline__ void nsa_compute(int cur, int buf, int t, int hl, u64 mymask, const bf16x8 (&Qf)[2][2], f32x4 (&O)[4][2], float (&m)[2], float (&l)[2],
;                                             const float (&inv)[2], float* impw, char* lds) {
;     ...
;     for (int ks = 0; ks < 2; ++ks)
; #pragma unroll
;       for (int kk = 0; kk < 2; ++kk) kfr[ks][kk] = *(const bf16x8*)(kt + (32 * s2 + 16 * kk + fr) * 128 + (((ks * 4 + fq) ^ (fr & 7)) << 4));
;     __builtin_amdgcn_s_setprio(1);
; #pragma unroll
;     for (int ks = 0; ks < 2; ++ks)
; #pragma unroll
;       for (int kk = 0; kk < 2; ++kk)
; #pragma unroll
;         for (int r = 0; r < 2; ++r) S[kk][r] = mfma16(kfr[ks][kk], Qf[r][ks], S[kk][r]);
;     __builtin_amdgcn_s_setprio(0);
;     bf16x8 Pf[2];
;     float g1s[2] = {0.f, 0.f}, p3s[2] = {0.f, 0.f};
; #pragma unroll
;     for (int r = 0; r < 2; ++r) {
;       float sv[2][4];
; #pragma unroll
;       for (int kk = 0; kk < 2; ++kk)
; #pragma unroll
;         for (int e = 0; e < 4; ++e) {
;           const int off = 32 * s2 + 16 * kk + e;
;           int idx;
;           if (MODE <= 1) { idx = base - 16 * off; idx = idx > 0 ? idx : 0; } else idx = base - off;
;     ...
;           for (int e = 0; e < 4; ++e) { pv[kk][e] = __builtin_amdgcn_exp2f(sv[kk][e] - me); ps += pv[kk][e]; }
;         l[r] += ps;
;       }
;       if (MODE != 0) {
;         const unsigned w0 = pk2(pv[0][0], pv[0][1]), w1 = pk2(pv[0][2], pv[0][3]), w2 = pk2(pv[1][0], pv[1][1]), w3 = pk2(pv[1][2], pv[1][3]);
;         u32x4 pw; pw.x = w0; pw.y = w1; pw.z = w2; pw.w = w3;
;         Pf[r] = __builtin_bit_cast(bf16x8, pw);
;       }
;     }
;     if (MODE != 0) {
;       bf16x8 vfr[4];
; #pragma unroll
;       for (int df = 0; df < 4; ++df) {
;         const bf16x4 va = *(const bf16x4*)(vt + (df * 16 + fr) * 68 + 32 * s2 + 4 * fq);
;         const bf16x4 vb = *(const bf16x4*)(vt + (df * 16 + fr) * 68 + 32 * s2 + 16 + 4 * fq);
;         bf16x8 vf; vf[0] = va[0]; vf[1] = va[1]; vf[2] = va[2]; vf[3] = va[3]; vf[4] = vb[0]; vf[5] = vb[1]; vf[6] = vb[2]; vf[7] = vb[3];
;         vfr[df] = vf;
;       }
;       __builtin_amdgcn_s_setprio(1);
; #pragma unroll
;       for (int df = 0; df < 4; ++df)
; #pragma unroll
;         for (int r = 0; r < 2; ++r) O[df][r] = mfma16(vfr[df], Pf[r], O[df][r]);
;       __builtin_amdgcn_s_setprio(0);
.LBB0_367:
	v_sub_f32_e32 v75, v81, v74
	v_exp_f32_e32 v75, v75
	v_sub_f32_e32 v80, v80, v74
	v_exp_f32_e32 v80, v80
	v_sub_f32_e32 v78, v78, v74
	v_exp_f32_e32 v78, v78
	v_sub_f32_e32 v81, v82, v74
	v_exp_f32_e32 v81, v81
	v_sub_f32_e32 v77, v77, v74
	v_add_f32_e32 v79, 0, v75
	v_exp_f32_e32 v77, v77
	v_sub_f32_e32 v76, v76, v74
	v_add_f32_e32 v79, v80, v79
	v_exp_f32_e32 v76, v76
	v_sub_f32_e32 v73, v73, v74
	v_add_f32_e32 v79, v78, v79
	v_exp_f32_e32 v73, v73
	v_sub_f32_e32 v72, v72, v74
	v_add_f32_e32 v79, v81, v79
	v_exp_f32_e32 v72, v72
	v_add_f32_e32 v79, v77, v79
	v_add_f32_e32 v79, v76, v79
	v_add_f32_e32 v79, v73, v79
	s_lshl_b32 s17, s46, 9
	v_add_f32_e32 v74, v72, v79
	v_cvt_pk_bf16_f32 v149, v73, v72
	v_mul_u32_u24_e32 v72, 0x44, v92
	s_add_i32 s43, s64, s17
	v_lshlrev_b32_e32 v72, 1, v72
	v_lshlrev_b32_e32 v73, 1, v93
	v_cvt_pk_bf16_f32 v146, v75, v80
	v_add3_u32 v80, s43, v72, v73
	v_add_u32_e32 v137, 0x4000, v80
	v_add_u32_e32 v138, 0x4800, v80
	v_add_f32_e32 v191, v191, v74
	v_cvt_pk_bf16_f32 v147, v78, v81
	v_cvt_pk_bf16_f32 v148, v77, v76
	ds_read2_b64 v[72:75], v137 offset1:4
	ds_read2_b64 v[76:79], v138 offset0:16 offset1:20
	v_add_u32_e32 v139, 0x5000, v80
	v_add_u32_e32 v140, 0x5800, v80
	ds_read2_b64 v[150:153], v139 offset0:32 offset1:36
	ds_read2_b64 v[154:157], v140 offset0:48 offset1:52
	v_cvt_pk_bf16_f32 v142, v85, v86
	v_cvt_pk_bf16_f32 v143, v87, v84
	v_cvt_pk_bf16_f32 v144, v89, v94
	v_cvt_pk_bf16_f32 v145, v95, v88
	s_waitcnt lgkmcnt(3)
	s_nop 0
	v_mfma_f32_16x16x32_bf16 v[84:87], v[72:75], v[142:145], v[116:119]
	v_mfma_f32_16x16x32_bf16 v[96:99], v[72:75], v[146:149], v[104:107]
	s_waitcnt lgkmcnt(2)
	v_mfma_f32_16x16x32_bf16 v[80:83], v[76:79], v[142:145], v[124:127]
	v_mfma_f32_16x16x32_bf16 v[92:95], v[76:79], v[146:149], v[108:111]
	s_waitcnt lgkmcnt(1)
	v_mfma_f32_16x16x32_bf16 v[76:79], v[150:153], v[142:145], v[128:131]
	v_mfma_f32_16x16x32_bf16 v[108:111], v[150:153], v[146:149], v[112:115]
	s_waitcnt lgkmcnt(0)
	v_mfma_f32_16x16x32_bf16 v[72:75], v[154:157], v[142:145], v[132:135]
	v_mfma_f32_16x16x32_bf16 v[104:107], v[154:157], v[146:149], v[120:123]
	v_add_u32_e32 v88, v91, v90
	v_add_u32_e32 v100, v100, v90
	ds_read_b128 v[112:115], v88 offset:4096
	ds_read_b128 v[116:119], v88 offset:6144
	ds_read_b128 v[88:91], v100 offset:4096
	ds_read_b128 v[120:123], v100 offset:6144
	v_add_u32_e32 v251, 0xa00, v136
	ds_read2_b32 v[168:169], v136 offset0:31 offset1:32
	ds_read2_b32 v[170:171], v136 offset0:29 offset1:30
	ds_read2_b32 v[172:173], v136 offset0:15 offset1:16
	ds_read2_b32 v[174:175], v136 offset0:13 offset1:14
	ds_read2_b32 v[198:199], v251 offset0:31 offset1:32
	ds_read2_b32 v[200:201], v251 offset0:29 offset1:30
	ds_read2_b32 v[202:203], v251 offset0:15 offset1:16
	ds_read2_b32 v[204:205], v251 offset0:13 offset1:14
	s_waitcnt lgkmcnt(11)
	v_mfma_f32_16x16x32_bf16 v[100:103], v[112:115], v[0:3], 0
	v_mfma_f32_16x16x32_bf16 v[112:115], v[112:115], v[8:11], 0
	s_waitcnt lgkmcnt(10)
	v_mfma_f32_16x16x32_bf16 v[124:127], v[116:119], v[0:3], 0
	v_mfma_f32_16x16x32_bf16 v[116:119], v[116:119], v[8:11], 0
	s_waitcnt lgkmcnt(9)
	v_mfma_f32_16x16x32_bf16 v[128:131], v[88:91], v[4:7], v[100:103]
	v_mfma_f32_16x16x32_bf16 v[100:103], v[88:91], v[12:15], v[112:115]
	s_waitcnt lgkmcnt(8)
	v_mfma_f32_16x16x32_bf16 v[88:91], v[120:123], v[12:15], v[116:119]
	v_mfma_f32_16x16x32_bf16 v[124:127], v[120:123], v[4:7], v[124:127]
	s_nop 0
	s_waitcnt lgkmcnt(7)
	s_nop 0
	s_nop 0
	v_fmamk_f32 v123, v128, 0x3e38aa3b, v169
	v_fmamk_f32 v118, v129, 0x3e38aa3b, v168
	s_waitcnt lgkmcnt(6)
	v_fmamk_f32 v122, v130, 0x3e38aa3b, v171
	v_fmamk_f32 v116, v131, 0x3e38aa3b, v170
	s_waitcnt lgkmcnt(5)
	v_fmamk_f32 v119, v124, 0x3e38aa3b, v173
	v_fmamk_f32 v114, v125, 0x3e38aa3b, v172
	s_waitcnt lgkmcnt(4)
	v_fmamk_f32 v113, v126, 0x3e38aa3b, v175
	v_fmamk_f32 v112, v127, 0x3e38aa3b, v174
	v_max3_f32 v115, v123, v118, v122
	v_max3_f32 v117, v116, v119, v114
	v_max_f32_e32 v120, v113, v112
	v_max3_f32 v115, v120, v115, v117
	v_add_f32_e32 v117, 0x41000000, v192
	v_cmp_gt_f32_e32 vcc, v115, v117
	s_cbranch_vccz .LBB0_369
	ds_bpermute_b32 v117, v233, v115
	v_max_f32_e32 v115, v115, v115
	v_mov_b32_e32 v121, v193
	s_waitcnt lgkmcnt(0)
	v_max_f32_e32 v117, v117, v117
	v_max_f32_e32 v115, v115, v117
	ds_bpermute_b32 v117, v234, v115
	s_waitcnt lgkmcnt(0)
	v_max3_f32 v120, v192, v115, v117
	v_sub_f32_e32 v115, v192, v120
	v_exp_f32_e32 v124, v115
	v_mov_b64_e32 v[192:193], v[120:121]
	v_mul_f32_e32 v190, v190, v124
	v_pk_mul_f32 v[86:87], v[86:87], v[124:125] op_sel_hi:[1,0]
	v_pk_mul_f32 v[84:85], v[84:85], v[124:125] op_sel_hi:[1,0]
	v_pk_mul_f32 v[82:83], v[82:83], v[124:125] op_sel_hi:[1,0]
	v_pk_mul_f32 v[80:81], v[80:81], v[124:125] op_sel_hi:[1,0]
	v_pk_mul_f32 v[78:79], v[78:79], v[124:125] op_sel_hi:[1,0]
	v_pk_mul_f32 v[76:77], v[76:77], v[124:125] op_sel_hi:[1,0]
	v_pk_mul_f32 v[74:75], v[74:75], v[124:125] op_sel_hi:[1,0]
	v_pk_mul_f32 v[72:73], v[72:73], v[124:125] op_sel_hi:[1,0]
	s_branch .LBB0_370

; #define TIDX opaque_tid()
; __device__ __forceinline__ unsigned pk2(float lo, float hi) { const f32x2v v = {lo, hi}; const bf16x2v r = __builtin_convertvector(v, bf16x2v); return __builtin_bit_cast(unsigned, r); }
; __device__ __forceinline__ f32x4 mfma16(bf16x8 a, bf16x8 b, f32x4 c) { return __builtin_amdgcn_mfma_f32_16x16x32_bf16(a, b, c, 0, 0, 0); }
; __device__ __forceinline__ void kv_lwrite(const KVRegs& r, char* lds, int buf) {
;   const int tid = TIDX, row = tid >> 3, cq = tid & 7;
;   char* kt = lds + NSA_KT + buf * 8192 + row * 128;
;   *(u32x4*)(kt + ((cq ^ (row & 7)) << 4)) = r.k0;
;   bf16_t* vt = (bf16_t*)(lds + NSA_VT + buf * 8704) + (cq * 8) * 68 + row;
; #pragma unroll
;   for (int i = 0; i < 4; ++i) { vt[(2 * i) * 68] = (bf16_t)(r.v0[i] & 0xffffu); vt[(2 * i + 1) * 68] = (bf16_t)(r.v0[i] >> 16); }
; }
; template <int MODE>
; __device__ __forceinline__ void nsa_compute(int cur, int buf, int t, int hl, u64 mymask, const bf16x8 (&Qf)[2][2], f32x4 (&O)[4][2], float (&m)[2], float (&l)[2],
;                                             const float (&inv)[2], float* impw, char* lds) {
;     ...
;         float ps = 0.f;
; #pragma unroll
;         for (int kk = 0; kk < 2; ++kk)
; #pragma unroll
;           for (int e = 0; e < 4; ++e) { pv[kk][e] = __builtin_amdgcn_exp2f(sv[kk][e] - me); ps += pv[kk][e]; }
;         l[r] += ps;
;       }
;       if (MODE != 0) {
;         const unsigned w0 = pk2(pv[0][0], pv[0][1]), w1 = pk2(pv[0][2], pv[0][3]), w2 = pk2(pv[1][0], pv[1][1]), w3 = pk2(pv[1][2], pv[1][3]);
;         u32x4 pw; pw.x = w0; pw.y = w1; pw.z = w2; pw.w = w3;
;         Pf[r] = __builtin_bit_cast(bf16x8, pw);
;       }
;     }
;     if (MODE != 0) {
;       bf16x8 vfr[4];
; #pragma unroll
;       for (int df = 0; df < 4; ++df) {
;         const bf16x4 va = *(const bf16x4*)(vt + (df * 16 + fr) * 68 + 32 * s2 + 4 * fq);
;         const bf16x4 vb = *(const bf16x4*)(vt + (df * 16 + fr) * 68 + 32 * s2 + 16 + 4 * fq);
;         bf16x8 vf; vf[0] = va[0]; vf[1] = va[1]; vf[2] = va[2]; vf[3] = va[3]; vf[4] = vb[0]; vf[5] = vb[1]; vf[6] = vb[2]; vf[7] = vb[3];
;         vfr[df] = vf;
;       }
;       __builtin_amdgcn_s_setprio(1);
; #pragma unroll
;       for (int df = 0; df < 4; ++df)
; #pragma unroll
;         for (int r = 0; r < 2; ++r) O[df][r] = mfma16(vfr[df], Pf[r], O[df][r]);
;       __builtin_amdgcn_s_setprio(0);
.LBB0_373:
	v_sub_f32_e32 v91, v113, v90
	v_exp_f32_e32 v113, v91
	v_sub_f32_e32 v91, v112, v90
	v_exp_f32_e32 v112, v91
	v_sub_f32_e32 v91, v101, v90
	v_cvt_pk_bf16_f32 v124, v119, v114
	v_exp_f32_e32 v114, v91
	v_sub_f32_e32 v91, v100, v90
	v_cvt_pk_bf16_f32 v122, v115, v117
	v_exp_f32_e32 v115, v91
	v_sub_f32_e32 v91, v103, v90
	v_cvt_pk_bf16_f32 v123, v118, v116
	v_exp_f32_e32 v116, v91
	v_sub_f32_e32 v91, v102, v90
	ds_read2_b64 v[100:103], v137 offset0:8 offset1:12
	ds_read2_b64 v[126:129], v138 offset0:24 offset1:28
	ds_read2_b64 v[130:133], v139 offset0:40 offset1:44
	ds_read2_b64 v[134:137], v140 offset0:56 offset1:60
	v_sub_f32_e32 v89, v89, v90
	v_sub_f32_e32 v88, v88, v90
	v_exp_f32_e32 v117, v91
	v_exp_f32_e32 v118, v89
	v_exp_f32_e32 v119, v88
	v_cvt_pk_bf16_f32 v125, v121, v120
	v_cvt_pk_bf16_f32 v138, v113, v112
	v_cvt_pk_bf16_f32 v139, v114, v115
	v_cvt_pk_bf16_f32 v140, v116, v117
	v_cvt_pk_bf16_f32 v141, v118, v119
	s_waitcnt lgkmcnt(3)
	v_mfma_f32_16x16x32_bf16 v[88:91], v[100:103], v[122:125], v[84:87]
	v_mfma_f32_16x16x32_bf16 v[96:99], v[100:103], v[138:141], v[96:99]
	s_waitcnt lgkmcnt(2)
	v_mfma_f32_16x16x32_bf16 v[100:103], v[126:129], v[122:125], v[80:83]
	v_mfma_f32_16x16x32_bf16 v[84:87], v[126:129], v[138:141], v[92:95]
	s_waitcnt lgkmcnt(1)
	v_mfma_f32_16x16x32_bf16 v[92:95], v[130:133], v[122:125], v[76:79]
	v_mfma_f32_16x16x32_bf16 v[76:79], v[130:133], v[138:141], v[108:111]
	s_waitcnt lgkmcnt(0)
	v_mfma_f32_16x16x32_bf16 v[80:83], v[134:137], v[122:125], v[72:75]
	v_mfma_f32_16x16x32_bf16 v[72:75], v[134:137], v[138:141], v[104:107]
	s_xor_b32 s46, s46, 1
	s_cmp_lt_i32 s16, 0
	s_cbranch_scc1 .LBB0_375
	v_mov_b32 v104, v179
	s_lshl_b32 s17, s46, 13
	v_ashrrev_i32_e32 v105, 3, v104
	v_xor_b32_e32 v107, v105, v104
	v_lshl_add_u32 v106, v105, 7, s17
	v_lshlrev_b32_e32 v107, 4, v107
	s_movk_i32 s30, 0x70
	v_lshlrev_b32_e32 v104, 3, v104
	v_and_or_b32 v106, v107, s30, v106
	s_lshl_b32 s30, s46, 9
	v_and_b32_e32 v104, 56, v104
	s_add_i32 s17, s17, s30
	v_mul_u32_u24_e32 v104, 0x88, v104
	v_lshlrev_b32_e32 v105, 1, v105
	v_add3_u32 v104, s17, v104, v105
	s_waitcnt vmcnt(1)
	ds_write_b128 v106, v[56:59]
	s_waitcnt vmcnt(0)
	ds_write_b16 v104, v60 offset:16384
	ds_write_b16_d16_hi v104, v60 offset:16520
	ds_write_b16 v104, v61 offset:16656
	ds_write_b16_d16_hi v104, v61 offset:16792
	ds_write_b16 v104, v62 offset:16928
	ds_write_b16_d16_hi v104, v62 offset:17064
	ds_write_b16 v104, v63 offset:17200
	ds_write_b16_d16_hi v104, v63 offset:17336

; __device__ __forceinline__ f32x4 mfma16(bf16x8 a, bf16x8 b, f32x4 c) { return __builtin_amdgcn_mfma_f32_16x16x32_bf16(a, b, c, 0, 0, 0); }
; template <int MODE>
; __device__ __forceinline__ void nsa_compute(int cur, int buf, int t, int hl, u64 mymask, const bf16x8 (&Qf)[2][2], f32x4 (&O)[4][2], float (&m)[2], float (&l)[2],
;                                             const float (&inv)[2], float* impw, char* lds) {
;     ...
;   const int base = (MODE <= 1) ? (t - 31 - 16 * (cur * 64 + 4 * fq) + 64) : (t - cur * 64 - 4 * fq + 64);
; #pragma unroll
;   for (int s2 = 0; s2 < 2; ++s2) {
;     f32x4 S[2][2] = {};
;     bf16x8 kfr[2][2];
; #pragma unroll
;     for (int ks = 0; ks < 2; ++ks)
; #pragma unroll
;       for (int kk = 0; kk < 2; ++kk) kfr[ks][kk] = *(const bf16x8*)(kt + (32 * s2 + 16 * kk + fr) * 128 + (((ks * 4 + fq) ^ (fr & 7)) << 4));
;     __builtin_amdgcn_s_setprio(1);
; #pragma unroll
;     for (int ks = 0; ks < 2; ++ks)
; #pragma unroll
;       for (int kk = 0; kk < 2; ++kk)
; #pragma unroll
;         for (int r = 0; r < 2; ++r) S[kk][r] = mfma16(kfr[ks][kk], Qf[r][ks], S[kk][r]);
;     __builtin_amdgcn_s_setprio(0);
;     bf16x8 Pf[2];
;     float g1s[2] = {0.f, 0.f}, p3s[2] = {0.f, 0.f};
; #pragma unroll
;     for (int r = 0; r < 2; ++r) {
;       float sv[2][4];
; #pragma unroll
;       for (int kk = 0; kk < 2; ++kk)
; #pragma unroll
;         for (int e = 0; e < 4; ++e) {
;           const int off = 32 * s2 + 16 * kk + e;
;           int idx;
;           if (MODE <= 1) { idx = base - 16 * off; idx = idx > 0 ? idx : 0; } else idx = base - off;
;           sv[kk][e] = S[kk][r][e] * (0.125f * LOG2E) + tb[r * TS + idx];
;         }
;     ...
;         float ps = 0.f;
; #pragma unroll
;         for (int kk = 0; kk < 2; ++kk)
; #pragma unroll
;           for (int e = 0; e < 4; ++e) { pv[kk][e] = __builtin_amdgcn_exp2f(sv[kk][e] - me); ps += pv[kk][e]; }
;         l[r] += ps;
.LBB0_377:
	v_add_f32_e32 v104, 0, v113
	v_add_f32_e32 v104, v112, v104
	v_add_f32_e32 v104, v114, v104
	v_add_f32_e32 v104, v115, v104
	v_add_f32_e32 v104, v116, v104
	v_add_f32_e32 v104, v117, v104
	v_add_f32_e32 v104, v118, v104
	v_add_f32_e32 v104, v119, v104
	s_cmp_lt_i32 s16, 0
	v_add_f32_e32 v195, v195, v104
	s_cbranch_scc1 .LBB0_380
	v_mov_b32 v104, v179
	s_lshl_b32 s71, s46, 13
	v_lshrrev_b32_e32 v105, 4, v104
	v_bfe_u32 v120, v104, 4, 2
	v_and_b32_e32 v112, 7, v104
	v_and_b32_e32 v149, 15, v104
	v_bitop3_b32 v104, v105, v112, 3 bitop3:0x6c
	v_bitop3_b32 v112, v120, v112, 4 bitop3:0x36
	v_lshlrev_b32_e32 v146, 7, v149
	v_lshl_or_b32 v147, v104, 4, s71
	v_lshl_or_b32 v148, v112, 4, s71
	v_or_b32_e32 v108, v147, v146
	v_or_b32_e32 v116, v148, v146
	ds_read_b128 v[104:107], v108
	ds_read_b128 v[108:111], v108 offset:2048
	ds_read_b128 v[112:115], v116
	ds_read_b128 v[116:119], v116 offset:2048
	v_lshlrev_b32_e32 v150, 2, v120
	v_sub_u32_e32 v251, v180, v150
	v_lshl_add_u32 v251, v251, 2, v235
	s_lshl_b32 s16, s16, 8
	v_subrev_u32_e32 v250, s16, v251
	v_add_u32_e32 v249, 0xa00, v250
	ds_read2_b32 v[198:199], v250 offset0:63 offset1:64
	ds_read2_b32 v[200:201], v250 offset0:61 offset1:62
	ds_read2_b32 v[202:203], v250 offset0:47 offset1:48
	ds_read2_b32 v[204:205], v250 offset0:45 offset1:46
	ds_read2_b32 v[206:207], v249 offset0:63 offset1:64
	ds_read2_b32 v[208:209], v249 offset0:61 offset1:62
	ds_read2_b32 v[210:211], v249 offset0:47 offset1:48
	ds_read2_b32 v[236:237], v249 offset0:45 offset1:46
	s_waitcnt lgkmcnt(11)
	v_mfma_f32_16x16x32_bf16 v[120:123], v[104:107], v[0:3], 0
	v_mfma_f32_16x16x32_bf16 v[104:107], v[104:107], v[8:11], 0
	s_waitcnt lgkmcnt(10)
	v_mfma_f32_16x16x32_bf16 v[128:131], v[108:111], v[0:3], 0
	v_mfma_f32_16x16x32_bf16 v[108:111], v[108:111], v[8:11], 0
	s_waitcnt lgkmcnt(9)
	v_mfma_f32_16x16x32_bf16 v[124:127], v[112:115], v[12:15], v[104:107]
	s_waitcnt lgkmcnt(8)
	v_mfma_f32_16x16x32_bf16 v[104:107], v[116:119], v[4:7], v[128:131]
	v_mfma_f32_16x16x32_bf16 v[116:119], v[116:119], v[12:15], v[108:111]
	v_mfma_f32_16x16x32_bf16 v[120:123], v[112:115], v[4:7], v[120:123]
	s_nop 0
	s_nop 0
	v_sub_u32_e32 v108, v180, v150
	v_lshl_add_u32 v108, v108, 2, v235
	v_subrev_u32_e32 v154, s16, v108
	s_waitcnt lgkmcnt(7)
	s_nop 1
	v_fmamk_f32 v135, v120, 0x3e38aa3b, v199
	v_fmamk_f32 v134, v121, 0x3e38aa3b, v198
	s_waitcnt lgkmcnt(6)
	v_fmamk_f32 v133, v122, 0x3e38aa3b, v201
	v_fmamk_f32 v132, v123, 0x3e38aa3b, v200
	s_waitcnt lgkmcnt(5)
	v_fmamk_f32 v129, v104, 0x3e38aa3b, v203
	v_fmamk_f32 v128, v105, 0x3e38aa3b, v202
	s_waitcnt lgkmcnt(4)
	v_fmamk_f32 v131, v106, 0x3e38aa3b, v205
	v_fmamk_f32 v130, v107, 0x3e38aa3b, v204
	v_max3_f32 v104, v135, v134, v133
	v_max3_f32 v105, v132, v129, v128
	v_max_f32_e32 v106, v131, v130
	v_max3_f32 v104, v106, v104, v105
	v_add_f32_e32 v105, 0x41000000, v192
	v_cmp_gt_f32_e32 vcc, v104, v105
	s_cbranch_vccz .LBB0_381
	ds_bpermute_b32 v105, v233, v104
	v_max_f32_e32 v104, v104, v104
	v_mov_b32_e32 v137, v193
	v_mov_b32_e32 v197, v195
	s_waitcnt lgkmcnt(0)
	v_max_f32_e32 v105, v105, v105
	v_max_f32_e32 v104, v104, v105
	ds_bpermute_b32 v105, v234, v104
	s_waitcnt lgkmcnt(0)
	v_max3_f32 v136, v192, v104, v105
	v_sub_f32_e32 v104, v192, v136
	v_exp_f32_e32 v120, v104
	v_mov_b64_e32 v[192:193], v[136:137]
	v_mul_f32_e32 v196, v194, v120
	v_pk_mul_f32 v[114:115], v[90:91], v[120:121] op_sel_hi:[1,0]
	v_pk_mul_f32 v[112:113], v[88:89], v[120:121] op_sel_hi:[1,0]
	v_pk_mul_f32 v[106:107], v[102:103], v[120:121] op_sel_hi:[1,0]
	v_pk_mul_f32 v[104:105], v[100:101], v[120:121] op_sel_hi:[1,0]
	v_pk_mul_f32 v[110:111], v[94:95], v[120:121] op_sel_hi:[1,0]
	v_pk_mul_f32 v[108:109], v[92:93], v[120:121] op_sel_hi:[1,0]
	v_pk_mul_f32 v[122:123], v[82:83], v[120:121] op_sel_hi:[1,0]
	v_pk_mul_f32 v[120:121], v[80:81], v[120:121] op_sel_hi:[1,0]
	s_branch .LBB0_382

; template <int MODE>
; __device__ __forceinline__ void nsa_compute(int cur, int buf, int t, int hl, u64 mymask, const bf16x8 (&Qf)[2][2], f32x4 (&O)[4][2], float (&m)[2], float (&l)[2],
;                                             const float (&inv)[2], float* impw, char* lds) {
;     ...
;     for (int ks = 0; ks < 2; ++ks)
; #pragma unroll
;       for (int kk = 0; kk < 2; ++kk) kfr[ks][kk] = *(const bf16x8*)(kt + (32 * s2 + 16 * kk + fr) * 128 + (((ks * 4 + fq) ^ (fr & 7)) << 4));
;     __builtin_amdgcn_s_setprio(1);
; #pragma unroll
;     for (int ks = 0; ks < 2; ++ks)
; #pragma unroll
;       for (int kk = 0; kk < 2; ++kk)
; #pragma unroll
;         for (int r = 0; r < 2; ++r) S[kk][r] = mfma16(kfr[ks][kk], Qf[r][ks], S[kk][r]);
;     __builtin_amdgcn_s_setprio(0);
;     bf16x8 Pf[2];
;     float g1s[2] = {0.f, 0.f}, p3s[2] = {0.f, 0.f};
; #pragma unroll
;     for (int r = 0; r < 2; ++r) {
;       float sv[2][4];
; #pragma unroll
;       for (int kk = 0; kk < 2; ++kk)
; #pragma unroll
;         for (int e = 0; e < 4; ++e) {
;           const int off = 32 * s2 + 16 * kk + e;
;           int idx;
;           if (MODE <= 1) { idx = base - 16 * off; idx = idx > 0 ? idx : 0; } else idx = base - off;
;     ...
;           for (int e = 0; e < 4; ++e) { pv[kk][e] = __builtin_amdgcn_exp2f(sv[kk][e] - me); ps += pv[kk][e]; }
;         l[r] += ps;
;       }
;       if (MODE != 0) {
;         const unsigned w0 = pk2(pv[0][0], pv[0][1]), w1 = pk2(pv[0][2], pv[0][3]), w2 = pk2(pv[1][0], pv[1][1]), w3 = pk2(pv[1][2], pv[1][3]);
;         u32x4 pw; pw.x = w0; pw.y = w1; pw.z = w2; pw.w = w3;
;         Pf[r] = __builtin_bit_cast(bf16x8, pw);
;       }
;     }
;     if (MODE != 0) {
;       bf16x8 vfr[4];
; #pragma unroll
;       for (int df = 0; df < 4; ++df) {
;         const bf16x4 va = *(const bf16x4*)(vt + (df * 16 + fr) * 68 + 32 * s2 + 4 * fq);
;         const bf16x4 vb = *(const bf16x4*)(vt + (df * 16 + fr) * 68 + 32 * s2 + 16 + 4 * fq);
;         bf16x8 vf; vf[0] = va[0]; vf[1] = va[1]; vf[2] = va[2]; vf[3] = va[3]; vf[4] = vb[0]; vf[5] = vb[1]; vf[6] = vb[2]; vf[7] = vb[3];
;         vfr[df] = vf;
;       }
;       __builtin_amdgcn_s_setprio(1);
; #pragma unroll
;       for (int df = 0; df < 4; ++df)
; #pragma unroll
;         for (int r = 0; r < 2; ++r) O[df][r] = mfma16(vfr[df], Pf[r], O[df][r]);
;       __builtin_amdgcn_s_setprio(0);
.LBB0_385:
	v_sub_f32_e32 v119, v135, v118
	v_exp_f32_e32 v119, v119
	v_sub_f32_e32 v134, v134, v118
	v_exp_f32_e32 v134, v134
	v_sub_f32_e32 v145, v145, v118
	v_exp_f32_e32 v145, v145
	v_sub_f32_e32 v144, v144, v118
	v_exp_f32_e32 v144, v144
	v_sub_f32_e32 v133, v133, v118
	v_add_f32_e32 v135, 0, v119
	v_exp_f32_e32 v133, v133
	v_sub_f32_e32 v132, v132, v118
	v_add_f32_e32 v135, v134, v135
	v_exp_f32_e32 v132, v132
	v_sub_f32_e32 v117, v117, v118
	v_add_f32_e32 v135, v145, v135
	v_exp_f32_e32 v117, v117
	v_sub_f32_e32 v116, v116, v118
	v_add_f32_e32 v135, v144, v135
	v_exp_f32_e32 v116, v116
	v_add_f32_e32 v135, v133, v135
	v_add_f32_e32 v135, v132, v135
	v_add_f32_e32 v135, v117, v135
	s_lshl_b32 s16, s46, 9
	v_add_f32_e32 v118, v116, v135
	v_cvt_pk_bf16_f32 v167, v117, v116
	v_mul_u32_u24_e32 v116, 0x44, v149
	s_add_i32 s72, s71, s16
	v_lshlrev_b32_e32 v116, 1, v116
	v_lshlrev_b32_e32 v117, 1, v150
	v_add3_u32 v116, s72, v116, v117
	v_cvt_pk_bf16_f32 v161, v153, v155
	v_cvt_pk_bf16_f32 v162, v156, v157
	v_add_u32_e32 v155, 0x4000, v116
	v_add_u32_e32 v156, 0x4800, v116
	v_cvt_pk_bf16_f32 v160, v151, v152
	v_cvt_pk_bf16_f32 v163, v158, v159
	v_cvt_pk_bf16_f32 v164, v119, v134
	v_cvt_pk_bf16_f32 v166, v133, v132
	ds_read2_b64 v[132:135], v155 offset1:4
	ds_read2_b64 v[150:153], v156 offset0:16 offset1:20
	v_add_u32_e32 v157, 0x5000, v116
	v_add_u32_e32 v158, 0x5800, v116
	ds_read2_b64 v[168:171], v157 offset0:32 offset1:36
	ds_read2_b64 v[172:175], v158 offset0:48 offset1:52
	v_add_f32_e32 v197, v197, v118
	v_cvt_pk_bf16_f32 v165, v145, v144
	s_waitcnt lgkmcnt(3)
	v_mfma_f32_16x16x32_bf16 v[116:119], v[132:135], v[160:163], v[112:115]
	v_mfma_f32_16x16x32_bf16 v[132:135], v[132:135], v[164:167], v[124:127]
	s_waitcnt lgkmcnt(2)
	v_mfma_f32_16x16x32_bf16 v[112:115], v[150:153], v[160:163], v[104:107]
	v_mfma_f32_16x16x32_bf16 v[128:131], v[150:153], v[164:167], v[128:131]
	s_waitcnt lgkmcnt(1)
	v_mfma_f32_16x16x32_bf16 v[108:111], v[168:171], v[160:163], v[108:111]
	v_mfma_f32_16x16x32_bf16 v[124:127], v[168:171], v[164:167], v[136:139]
	s_waitcnt lgkmcnt(0)
	v_mfma_f32_16x16x32_bf16 v[104:107], v[172:175], v[160:163], v[120:123]
	v_mfma_f32_16x16x32_bf16 v[120:123], v[172:175], v[164:167], v[140:143]
	s_nop 1
	s_nop 0
	v_add_u32_e32 v140, v147, v146
	v_add_u32_e32 v148, v148, v146
	ds_read_b128 v[136:139], v140 offset:4096
	ds_read_b128 v[140:143], v140 offset:6144
	ds_read_b128 v[144:147], v148 offset:4096
	ds_read_b128 v[148:151], v148 offset:6144
	v_add_u32_e32 v251, 0xa00, v154
	ds_read2_b32 v[202:203], v154 offset0:31 offset1:32
	ds_read2_b32 v[204:205], v154 offset0:29 offset1:30
	ds_read2_b32 v[206:207], v154 offset0:15 offset1:16
	ds_read2_b32 v[208:209], v154 offset0:13 offset1:14
	ds_read2_b32 v[210:211], v251 offset0:31 offset1:32
	ds_read2_b32 v[236:237], v251 offset0:29 offset1:30
	ds_read2_b32 v[238:239], v251 offset0:15 offset1:16
	ds_read2_b32 v[240:241], v251 offset0:13 offset1:14
	s_waitcnt lgkmcnt(11)
	v_mfma_f32_16x16x32_bf16 v[160:163], v[136:139], v[0:3], 0
	v_mfma_f32_16x16x32_bf16 v[136:139], v[136:139], v[8:11], 0
	s_waitcnt lgkmcnt(10)
	v_mfma_f32_16x16x32_bf16 v[168:171], v[140:143], v[8:11], 0
	v_mfma_f32_16x16x32_bf16 v[164:167], v[140:143], v[0:3], 0
	s_waitcnt lgkmcnt(9)
	v_mfma_f32_16x16x32_bf16 v[160:163], v[144:147], v[4:7], v[160:163]
	v_mfma_f32_16x16x32_bf16 v[140:143], v[144:147], v[12:15], v[136:139]
	s_waitcnt lgkmcnt(8)
	v_mfma_f32_16x16x32_bf16 v[136:139], v[148:151], v[12:15], v[168:171]
	v_mfma_f32_16x16x32_bf16 v[164:167], v[148:151], v[4:7], v[164:167]
	s_waitcnt lgkmcnt(7)
	s_nop 1
	s_nop 0
	v_fmamk_f32 v160, v160, 0x3e38aa3b, v203
	v_fmamk_f32 v150, v161, 0x3e38aa3b, v202
	s_waitcnt lgkmcnt(6)
	v_fmamk_f32 v159, v162, 0x3e38aa3b, v205
	v_fmamk_f32 v148, v163, 0x3e38aa3b, v204
	s_waitcnt lgkmcnt(5)
	v_fmamk_f32 v151, v164, 0x3e38aa3b, v207
	v_fmamk_f32 v146, v165, 0x3e38aa3b, v206
	s_waitcnt lgkmcnt(4)
	v_fmamk_f32 v145, v166, 0x3e38aa3b, v209
	v_fmamk_f32 v144, v167, 0x3e38aa3b, v208
	v_max3_f32 v147, v160, v150, v159
	v_max3_f32 v149, v148, v151, v146
	v_max_f32_e32 v152, v145, v144
	v_max3_f32 v147, v152, v147, v149
	v_add_f32_e32 v149, 0x41000000, v192
	v_cmp_gt_f32_e32 vcc, v147, v149
	s_cbranch_vccz .LBB0_387
	ds_bpermute_b32 v149, v233, v147
	v_max_f32_e32 v147, v147, v147
	v_mov_b32_e32 v153, v193
	s_waitcnt lgkmcnt(0)
	v_max_f32_e32 v149, v149, v149
	v_max_f32_e32 v147, v147, v149
	ds_bpermute_b32 v149, v234, v147
	s_waitcnt lgkmcnt(0)
	v_max3_f32 v152, v192, v147, v149
	v_sub_f32_e32 v147, v192, v152
	v_exp_f32_e32 v162, v147
	v_mov_b64_e32 v[192:193], v[152:153]
	v_mul_f32_e32 v196, v196, v162
	v_pk_mul_f32 v[118:119], v[118:119], v[162:163] op_sel_hi:[1,0]
	v_pk_mul_f32 v[116:117], v[116:117], v[162:163] op_sel_hi:[1,0]
	v_pk_mul_f32 v[114:115], v[114:115], v[162:163] op_sel_hi:[1,0]
	v_pk_mul_f32 v[112:113], v[112:113], v[162:163] op_sel_hi:[1,0]
	v_pk_mul_f32 v[110:111], v[110:111], v[162:163] op_sel_hi:[1,0]
	v_pk_mul_f32 v[108:109], v[108:109], v[162:163] op_sel_hi:[1,0]
	v_pk_mul_f32 v[106:107], v[106:107], v[162:163] op_sel_hi:[1,0]
	v_pk_mul_f32 v[104:105], v[104:105], v[162:163] op_sel_hi:[1,0]
	s_branch .LBB0_388

; #define TIDX opaque_tid()
; __device__ __forceinline__ unsigned pk2(float lo, float hi) { const f32x2v v = {lo, hi}; const bf16x2v r = __builtin_convertvector(v, bf16x2v); return __builtin_bit_cast(unsigned, r); }
; __device__ __forceinline__ f32x4 mfma16(bf16x8 a, bf16x8 b, f32x4 c) { return __builtin_amdgcn_mfma_f32_16x16x32_bf16(a, b, c, 0, 0, 0); }
; __device__ __forceinline__ void kv_lwrite(const KVRegs& r, char* lds, int buf) {
;   const int tid = TIDX, row = tid >> 3, cq = tid & 7;
;   char* kt = lds + NSA_KT + buf * 8192 + row * 128;
;   *(u32x4*)(kt + ((cq ^ (row & 7)) << 4)) = r.k0;
;   bf16_t* vt = (bf16_t*)(lds + NSA_VT + buf * 8704) + (cq * 8) * 68 + row;
; #pragma unroll
;   for (int i = 0; i < 4; ++i) { vt[(2 * i) * 68] = (bf16_t)(r.v0[i] & 0xffffu); vt[(2 * i + 1) * 68] = (bf16_t)(r.v0[i] >> 16); }
; }
; template <int MODE>
; __device__ __forceinline__ void nsa_compute(int cur, int buf, int t, int hl, u64 mymask, const bf16x8 (&Qf)[2][2], f32x4 (&O)[4][2], float (&m)[2], float (&l)[2],
;                                             const float (&inv)[2], float* impw, char* lds) {
;     ...
;         float ps = 0.f;
; #pragma unroll
;         for (int kk = 0; kk < 2; ++kk)
; #pragma unroll
;           for (int e = 0; e < 4; ++e) { pv[kk][e] = __builtin_amdgcn_exp2f(sv[kk][e] - me); ps += pv[kk][e]; }
;         l[r] += ps;
;       }
;       if (MODE != 0) {
;         const unsigned w0 = pk2(pv[0][0], pv[0][1]), w1 = pk2(pv[0][2], pv[0][3]), w2 = pk2(pv[1][0], pv[1][1]), w3 = pk2(pv[1][2], pv[1][3]);
;         u32x4 pw; pw.x = w0; pw.y = w1; pw.z = w2; pw.w = w3;
;         Pf[r] = __builtin_bit_cast(bf16x8, pw);
;       }
;     }
;     if (MODE != 0) {
;       bf16x8 vfr[4];
; #pragma unroll
;       for (int df = 0; df < 4; ++df) {
;         const bf16x4 va = *(const bf16x4*)(vt + (df * 16 + fr) * 68 + 32 * s2 + 4 * fq);
;         const bf16x4 vb = *(const bf16x4*)(vt + (df * 16 + fr) * 68 + 32 * s2 + 16 + 4 * fq);
;         bf16x8 vf; vf[0] = va[0]; vf[1] = va[1]; vf[2] = va[2]; vf[3] = va[3]; vf[4] = vb[0]; vf[5] = vb[1]; vf[6] = vb[2]; vf[7] = vb[3];
;         vfr[df] = vf;
;       }
;       __builtin_amdgcn_s_setprio(1);
; #pragma unroll
;       for (int df = 0; df < 4; ++df)
; #pragma unroll
;         for (int r = 0; r < 2; ++r) O[df][r] = mfma16(vfr[df], Pf[r], O[df][r]);
;       __builtin_amdgcn_s_setprio(0);
.LBB0_391:
	v_sub_f32_e32 v139, v145, v138
	v_exp_f32_e32 v168, v139
	v_sub_f32_e32 v139, v144, v138
	v_exp_f32_e32 v169, v139
	v_sub_f32_e32 v139, v141, v138
	v_exp_f32_e32 v170, v139
	v_sub_f32_e32 v139, v140, v138
	v_exp_f32_e32 v171, v139
	v_sub_f32_e32 v139, v143, v138
	v_cvt_pk_bf16_f32 v164, v147, v149
	v_cvt_pk_bf16_f32 v165, v150, v148
	v_cvt_pk_bf16_f32 v166, v151, v146
	v_cvt_pk_bf16_f32 v167, v153, v152
	v_exp_f32_e32 v172, v139
	v_sub_f32_e32 v139, v142, v138
	ds_read2_b64 v[140:143], v155 offset0:8 offset1:12
	ds_read2_b64 v[144:147], v156 offset0:24 offset1:28
	ds_read2_b64 v[148:151], v157 offset0:40 offset1:44
	ds_read2_b64 v[152:155], v158 offset0:56 offset1:60
	v_sub_f32_e32 v137, v137, v138
	v_sub_f32_e32 v136, v136, v138
	v_exp_f32_e32 v173, v139
	v_exp_f32_e32 v174, v137
	v_exp_f32_e32 v175, v136
	v_cvt_pk_bf16_f32 v198, v168, v169
	v_cvt_pk_bf16_f32 v199, v170, v171
	v_cvt_pk_bf16_f32 v200, v172, v173
	v_cvt_pk_bf16_f32 v201, v174, v175
	s_waitcnt lgkmcnt(3)
	v_mfma_f32_16x16x32_bf16 v[136:139], v[140:143], v[164:167], v[116:119]
	v_mfma_f32_16x16x32_bf16 v[140:143], v[140:143], v[198:201], v[132:135]
	s_waitcnt lgkmcnt(2)
	v_mfma_f32_16x16x32_bf16 v[156:159], v[144:147], v[164:167], v[112:115]
	v_mfma_f32_16x16x32_bf16 v[144:147], v[144:147], v[198:201], v[128:131]
	s_waitcnt lgkmcnt(1)
	v_mfma_f32_16x16x32_bf16 v[160:163], v[148:151], v[164:167], v[108:111]
	v_mfma_f32_16x16x32_bf16 v[148:151], v[148:151], v[198:201], v[124:127]
	s_waitcnt lgkmcnt(0)
	v_mfma_f32_16x16x32_bf16 v[164:167], v[152:155], v[164:167], v[104:107]
	v_mfma_f32_16x16x32_bf16 v[152:155], v[152:155], v[198:201], v[120:123]
	s_cmp_lt_i32 s42, 0
	s_cbranch_scc1 .LBB0_393
	v_mov_b32 v104, v179
	s_nop 0
	v_ashrrev_i32_e32 v105, 3, v104
	v_xor_b32_e32 v107, v105, v104
	v_lshlrev_b32_e32 v104, 3, v104
	v_lshlrev_b32_e32 v107, 4, v107
	v_and_b32_e32 v104, 56, v104
	v_lshlrev_b32_e32 v106, 7, v105
	v_and_b32_e32 v107, 0x70, v107
	v_mul_u32_u24_e32 v104, 0x88, v104
	v_lshlrev_b32_e32 v105, 1, v105
	v_add3_u32 v106, s64, v106, v107
	v_add3_u32 v104, s43, v104, v105
	s_waitcnt vmcnt(1)
	ds_write_b128 v106, v[64:67]
	s_waitcnt vmcnt(0)
	ds_write_b16 v104, v68 offset:16384
	ds_write_b16_d16_hi v104, v68 offset:16520
	ds_write_b16 v104, v69 offset:16656
	ds_write_b16_d16_hi v104, v69 offset:16792
	ds_write_b16 v104, v70 offset:16928
	ds_write_b16_d16_hi v104, v70 offset:17064
	ds_write_b16 v104, v71 offset:17200
	ds_write_b16_d16_hi v104, v71 offset:17336

; __device__ __forceinline__ f32x4 mfma16(bf16x8 a, bf16x8 b, f32x4 c) { return __builtin_amdgcn_mfma_f32_16x16x32_bf16(a, b, c, 0, 0, 0); }
; template <int MODE>
; __device__ __forceinline__ void nsa_compute(int cur, int buf, int t, int hl, u64 mymask, const bf16x8 (&Qf)[2][2], f32x4 (&O)[4][2], float (&m)[2], float (&l)[2],
;                                             const float (&inv)[2], float* impw, char* lds) {
;     ...
;   const int base = (MODE <= 1) ? (t - 31 - 16 * (cur * 64 + 4 * fq) + 64) : (t - cur * 64 - 4 * fq + 64);
; #pragma unroll
;   for (int s2 = 0; s2 < 2; ++s2) {
;     f32x4 S[2][2] = {};
;     bf16x8 kfr[2][2];
; #pragma unroll
;     for (int ks = 0; ks < 2; ++ks)
; #pragma unroll
;       for (int kk = 0; kk < 2; ++kk) kfr[ks][kk] = *(const bf16x8*)(kt + (32 * s2 + 16 * kk + fr) * 128 + (((ks * 4 + fq) ^ (fr & 7)) << 4));
;     __builtin_amdgcn_s_setprio(1);
; #pragma unroll
;     for (int ks = 0; ks < 2; ++ks)
; #pragma unroll
;       for (int kk = 0; kk < 2; ++kk)
; #pragma unroll
;         for (int r = 0; r < 2; ++r) S[kk][r] = mfma16(kfr[ks][kk], Qf[r][ks], S[kk][r]);
;     __builtin_amdgcn_s_setprio(0);
;     bf16x8 Pf[2];
;     float g1s[2] = {0.f, 0.f}, p3s[2] = {0.f, 0.f};
; #pragma unroll
;     for (int r = 0; r < 2; ++r) {
;       float sv[2][4];
; #pragma unroll
;       for (int kk = 0; kk < 2; ++kk)
; #pragma unroll
;         for (int e = 0; e < 4; ++e) {
;           const int off = 32 * s2 + 16 * kk + e;
;           int idx;
;           if (MODE <= 1) { idx = base - 16 * off; idx = idx > 0 ? idx : 0; } else idx = base - off;
;           sv[kk][e] = S[kk][r][e] * (0.125f * LOG2E) + tb[r * TS + idx];
;         }
;     ...
;         float ps = 0.f;
; #pragma unroll
;         for (int kk = 0; kk < 2; ++kk)
; #pragma unroll
;           for (int e = 0; e < 4; ++e) { pv[kk][e] = __builtin_amdgcn_exp2f(sv[kk][e] - me); ps += pv[kk][e]; }
;         l[r] += ps;
.LBB0_395:
	v_add_f32_e32 v104, 0, v168
	v_add_f32_e32 v104, v169, v104
	v_add_f32_e32 v104, v170, v104
	v_add_f32_e32 v104, v171, v104
	v_add_f32_e32 v104, v172, v104
	v_add_f32_e32 v104, v173, v104
	v_add_f32_e32 v104, v174, v104
	v_add_f32_e32 v104, v175, v104
	v_add_f32_e32 v197, v197, v104
	s_mov_b64 s[30:31], -1
	s_cmp_lt_i32 s42, 0
	s_mov_b64 s[36:37], -1
	s_cbranch_scc1 .LBB0_413
	v_mov_b32 v104, v179
	s_nop 0
	v_lshrrev_b32_e32 v105, 4, v104
	v_bfe_u32 v112, v104, 4, 2
	v_and_b32_e32 v113, 7, v104
	v_and_b32_e32 v200, 15, v104
	v_lshlrev_b32_e32 v201, 2, v112
	v_bitop3_b32 v104, v105, v113, 3 bitop3:0x6c
	v_bitop3_b32 v112, v112, v113, 4 bitop3:0x36
	v_lshlrev_b32_e32 v114, 7, v200
	v_lshl_add_u32 v104, v104, 4, s64
	v_lshl_add_u32 v112, v112, 4, s64
	v_add_u32_e32 v198, v104, v114
	v_add_u32_e32 v199, v112, v114
	ds_read_b128 v[104:107], v198
	ds_read_b128 v[108:111], v198 offset:2048
	ds_read_b128 v[112:115], v199
	ds_read_b128 v[116:119], v199 offset:2048
	s_waitcnt lgkmcnt(3)
	v_mfma_f32_16x16x32_bf16 v[120:123], v[104:107], v[0:3], 0
	v_mfma_f32_16x16x32_bf16 v[104:107], v[104:107], v[8:11], 0
	s_waitcnt lgkmcnt(2)
	v_mfma_f32_16x16x32_bf16 v[128:131], v[108:111], v[0:3], 0
	v_mfma_f32_16x16x32_bf16 v[108:111], v[108:111], v[8:11], 0
	s_waitcnt lgkmcnt(1)
	v_mfma_f32_16x16x32_bf16 v[168:171], v[112:115], v[4:7], v[120:123]
	v_mfma_f32_16x16x32_bf16 v[124:127], v[112:115], v[12:15], v[104:107]
	s_waitcnt lgkmcnt(0)
	v_mfma_f32_16x16x32_bf16 v[104:107], v[116:119], v[4:7], v[128:131]
	v_mfma_f32_16x16x32_bf16 v[120:123], v[116:119], v[12:15], v[108:111]
	s_nop 1
	s_nop 0
	v_sub_u32_e32 v108, v180, v201
	v_lshl_add_u32 v108, v108, 2, v235
	s_lshl_b32 s30, s42, 8
	v_subrev_u32_e32 v176, s30, v108
	ds_read2_b32 v[134:135], v176 offset0:63 offset1:64
	ds_read2_b32 v[132:133], v176 offset0:61 offset1:62
	ds_read2_b32 v[128:129], v176 offset0:47 offset1:48
	ds_read2_b32 v[130:131], v176 offset0:45 offset1:46
	s_waitcnt lgkmcnt(3)
	v_fmamk_f32 v135, v168, 0x3e38aa3b, v135
	v_fmac_f32_e32 v134, 0x3e38aa3b, v169
	s_waitcnt lgkmcnt(2)
	v_fmamk_f32 v133, v170, 0x3e38aa3b, v133
	v_fmac_f32_e32 v132, 0x3e38aa3b, v171
	s_waitcnt lgkmcnt(1)
	v_fmamk_f32 v129, v104, 0x3e38aa3b, v129
	v_fmac_f32_e32 v128, 0x3e38aa3b, v105
	s_waitcnt lgkmcnt(0)
	v_fmamk_f32 v131, v106, 0x3e38aa3b, v131
	v_fmac_f32_e32 v130, 0x3e38aa3b, v107
	v_max3_f32 v104, v135, v134, v133
	v_max3_f32 v105, v132, v129, v128
	v_max_f32_e32 v106, v131, v130
	v_max3_f32 v104, v106, v104, v105
	v_add_f32_e32 v105, 0x41000000, v192
	v_cmp_gt_f32_e32 vcc, v104, v105
	s_cbranch_vccz .LBB0_398
	ds_bpermute_b32 v105, v233, v104
	v_max_f32_e32 v104, v104, v104
	v_mov_b32_e32 v169, v193
	v_mov_b32_e32 v191, v197
	s_waitcnt lgkmcnt(0)
	v_max_f32_e32 v105, v105, v105
	v_max_f32_e32 v104, v104, v105
	ds_bpermute_b32 v105, v234, v104
	s_waitcnt lgkmcnt(0)
	v_max3_f32 v168, v192, v104, v105
	v_sub_f32_e32 v104, v192, v168
	v_exp_f32_e32 v116, v104
	v_mov_b64_e32 v[192:193], v[168:169]
	v_mul_f32_e32 v190, v196, v116
	v_pk_mul_f32 v[106:107], v[138:139], v[116:117] op_sel_hi:[1,0]
	v_pk_mul_f32 v[104:105], v[136:137], v[116:117] op_sel_hi:[1,0]
	v_pk_mul_f32 v[110:111], v[158:159], v[116:117] op_sel_hi:[1,0]
	v_pk_mul_f32 v[108:109], v[156:157], v[116:117] op_sel_hi:[1,0]
	v_pk_mul_f32 v[114:115], v[162:163], v[116:117] op_sel_hi:[1,0]
	v_pk_mul_f32 v[112:113], v[160:161], v[116:117] op_sel_hi:[1,0]
	v_pk_mul_f32 v[118:119], v[166:167], v[116:117] op_sel_hi:[1,0]
	v_pk_mul_f32 v[116:117], v[164:165], v[116:117] op_sel_hi:[1,0]
	s_branch .LBB0_399

; template <int MODE>
; __device__ __forceinline__ void nsa_compute(int cur, int buf, int t, int hl, u64 mymask, const bf16x8 (&Qf)[2][2], f32x4 (&O)[4][2], float (&m)[2], float (&l)[2],
;                                             const float (&inv)[2], float* impw, char* lds) {
;     ...
;     for (int ks = 0; ks < 2; ++ks)
; #pragma unroll
;       for (int kk = 0; kk < 2; ++kk) kfr[ks][kk] = *(const bf16x8*)(kt + (32 * s2 + 16 * kk + fr) * 128 + (((ks * 4 + fq) ^ (fr & 7)) << 4));
;     __builtin_amdgcn_s_setprio(1);
; #pragma unroll
;     for (int ks = 0; ks < 2; ++ks)
; #pragma unroll
;       for (int kk = 0; kk < 2; ++kk)
; #pragma unroll
;         for (int r = 0; r < 2; ++r) S[kk][r] = mfma16(kfr[ks][kk], Qf[r][ks], S[kk][r]);
;     __builtin_amdgcn_s_setprio(0);
;     bf16x8 Pf[2];
;     float g1s[2] = {0.f, 0.f}, p3s[2] = {0.f, 0.f};
; #pragma unroll
;     for (int r = 0; r < 2; ++r) {
;       float sv[2][4];
; #pragma unroll
;       for (int kk = 0; kk < 2; ++kk)
; #pragma unroll
;         for (int e = 0; e < 4; ++e) {
;           const int off = 32 * s2 + 16 * kk + e;
;           int idx;
;           if (MODE <= 1) { idx = base - 16 * off; idx = idx > 0 ? idx : 0; } else idx = base - off;
;     ...
;           for (int e = 0; e < 4; ++e) { pv[kk][e] = __builtin_amdgcn_exp2f(sv[kk][e] - me); ps += pv[kk][e]; }
;         l[r] += ps;
;       }
;       if (MODE != 0) {
;         const unsigned w0 = pk2(pv[0][0], pv[0][1]), w1 = pk2(pv[0][2], pv[0][3]), w2 = pk2(pv[1][0], pv[1][1]), w3 = pk2(pv[1][2], pv[1][3]);
;         u32x4 pw; pw.x = w0; pw.y = w1; pw.z = w2; pw.w = w3;
;         Pf[r] = __builtin_bit_cast(bf16x8, pw);
;       }
;     }
;     if (MODE != 0) {
;       bf16x8 vfr[4];
; #pragma unroll
;       for (int df = 0; df < 4; ++df) {
;         const bf16x4 va = *(const bf16x4*)(vt + (df * 16 + fr) * 68 + 32 * s2 + 4 * fq);
;         const bf16x4 vb = *(const bf16x4*)(vt + (df * 16 + fr) * 68 + 32 * s2 + 16 + 4 * fq);
;         bf16x8 vf; vf[0] = va[0]; vf[1] = va[1]; vf[2] = va[2]; vf[3] = va[3]; vf[4] = vb[0]; vf[5] = vb[1]; vf[6] = vb[2]; vf[7] = vb[3];
;         vfr[df] = vf;
;       }
;       __builtin_amdgcn_s_setprio(1);
; #pragma unroll
;       for (int df = 0; df < 4; ++df)
; #pragma unroll
;         for (int r = 0; r < 2; ++r) O[df][r] = mfma16(vfr[df], Pf[r], O[df][r]);
;       __builtin_amdgcn_s_setprio(0);
.LBB0_402:
	v_sub_f32_e32 v173, v173, v238
	v_exp_f32_e32 v173, v173
	v_sub_f32_e32 v172, v172, v238
	v_exp_f32_e32 v172, v172
	v_sub_f32_e32 v175, v175, v238
	v_exp_f32_e32 v175, v175
	v_sub_f32_e32 v174, v174, v238
	v_exp_f32_e32 v174, v174
	v_sub_f32_e32 v125, v125, v238
	v_cvt_pk_bf16_f32 v202, v202, v203
	v_cvt_pk_bf16_f32 v203, v204, v205
	v_cvt_pk_bf16_f32 v204, v206, v207
	v_add_f32_e32 v206, 0, v173
	v_exp_f32_e32 v125, v125
	v_sub_f32_e32 v124, v124, v238
	v_add_f32_e32 v206, v172, v206
	v_exp_f32_e32 v124, v124
	v_add_f32_e32 v206, v175, v206
	v_add_f32_e32 v206, v174, v206
	v_sub_f32_e32 v127, v127, v238
	v_add_f32_e32 v206, v125, v206
	v_exp_f32_e32 v127, v127
	v_sub_f32_e32 v126, v126, v238
	v_add_f32_e32 v206, v124, v206
	v_exp_f32_e32 v126, v126
	v_cvt_pk_bf16_f32 v172, v173, v172
	v_cvt_pk_bf16_f32 v173, v175, v174
	v_cvt_pk_bf16_f32 v174, v125, v124
	v_mul_u32_u24_e32 v124, 0x44, v200
	v_lshlrev_b32_e32 v124, 1, v124
	v_lshlrev_b32_e32 v125, 1, v201
	v_add3_u32 v200, s43, v124, v125
	v_cvt_pk_bf16_f32 v205, v236, v237
	v_add_f32_e32 v206, v127, v206
	v_add_u32_e32 v236, 0x4000, v200
	v_add_u32_e32 v237, 0x4800, v200
	v_add_f32_e32 v206, v126, v206
	v_cvt_pk_bf16_f32 v175, v127, v126
	ds_read2_b64 v[124:127], v236 offset1:4
	ds_read2_b64 v[240:243], v237 offset0:16 offset1:20
	v_add_u32_e32 v238, 0x5000, v200
	v_add_u32_e32 v239, 0x5800, v200
	ds_read2_b64 v[244:247], v238 offset0:32 offset1:36
	ds_read2_b64 v[248:251], v239 offset0:48 offset1:52
	v_add_f32_e32 v191, v191, v206
	s_waitcnt lgkmcnt(3)
	v_mfma_f32_16x16x32_bf16 v[104:107], v[124:127], v[202:205], v[104:107]
	v_mfma_f32_16x16x32_bf16 v[124:127], v[124:127], v[172:175], v[120:123]
	s_waitcnt lgkmcnt(2)
	v_mfma_f32_16x16x32_bf16 v[108:111], v[240:243], v[202:205], v[108:111]
	v_mfma_f32_16x16x32_bf16 v[128:131], v[240:243], v[172:175], v[128:131]
	s_waitcnt lgkmcnt(1)
	v_mfma_f32_16x16x32_bf16 v[112:115], v[244:247], v[202:205], v[112:115]
	v_mfma_f32_16x16x32_bf16 v[132:135], v[244:247], v[172:175], v[132:135]
	s_waitcnt lgkmcnt(0)
	v_mfma_f32_16x16x32_bf16 v[120:123], v[248:251], v[202:205], v[116:119]
	v_mfma_f32_16x16x32_bf16 v[168:171], v[248:251], v[172:175], v[168:171]
	s_nop 0
	ds_read_b128 v[116:119], v198 offset:4096
	ds_read_b128 v[172:175], v198 offset:6144
	ds_read_b128 v[200:203], v199 offset:4096
	ds_read_b128 v[204:207], v199 offset:6144
	s_waitcnt lgkmcnt(3)
	v_mfma_f32_16x16x32_bf16 v[240:243], v[116:119], v[0:3], 0
	v_mfma_f32_16x16x32_bf16 v[116:119], v[116:119], v[8:11], 0
	s_waitcnt lgkmcnt(2)
	v_mfma_f32_16x16x32_bf16 v[248:251], v[172:175], v[8:11], 0
	v_mfma_f32_16x16x32_bf16 v[244:247], v[172:175], v[0:3], 0
	s_waitcnt lgkmcnt(1)
	v_mfma_f32_16x16x32_bf16 v[172:175], v[200:203], v[12:15], v[116:119]
	s_waitcnt lgkmcnt(0)
	v_mfma_f32_16x16x32_bf16 v[116:119], v[204:207], v[12:15], v[248:251]
	v_mfma_f32_16x16x32_bf16 v[208:211], v[200:203], v[4:7], v[240:243]
	v_mfma_f32_16x16x32_bf16 v[242:245], v[204:207], v[4:7], v[244:247]
	ds_read2_b32 v[204:205], v176 offset0:31 offset1:32
	ds_read2_b32 v[202:203], v176 offset0:29 offset1:30
	ds_read2_b32 v[200:201], v176 offset0:15 offset1:16
	ds_read2_b32 v[198:199], v176 offset0:13 offset1:14
	s_waitcnt lgkmcnt(3)
	s_nop 0
	s_nop 0
	v_fmamk_f32 v241, v208, 0x3e38aa3b, v205
	v_fmac_f32_e32 v204, 0x3e38aa3b, v209
	s_waitcnt lgkmcnt(2)
	v_fmamk_f32 v240, v210, 0x3e38aa3b, v203
	v_fmac_f32_e32 v202, 0x3e38aa3b, v211
	s_waitcnt lgkmcnt(1)
	v_fmamk_f32 v205, v242, 0x3e38aa3b, v201
	v_fmac_f32_e32 v200, 0x3e38aa3b, v243
	s_waitcnt lgkmcnt(0)
	v_fmamk_f32 v199, v244, 0x3e38aa3b, v199
	v_fmac_f32_e32 v198, 0x3e38aa3b, v245
	v_max3_f32 v201, v241, v204, v240
	v_max3_f32 v203, v202, v205, v200
	v_max_f32_e32 v206, v199, v198
	v_max3_f32 v201, v206, v201, v203
	v_add_f32_e32 v203, 0x41000000, v192
	v_cmp_gt_f32_e32 vcc, v201, v203
	s_cbranch_vccz .LBB0_404
	ds_bpermute_b32 v203, v233, v201
	v_max_f32_e32 v201, v201, v201
	v_mov_b32_e32 v207, v193
	s_waitcnt lgkmcnt(0)
	v_max_f32_e32 v203, v203, v203
	v_max_f32_e32 v201, v201, v203
	ds_bpermute_b32 v203, v234, v201
	s_waitcnt lgkmcnt(0)
	v_max3_f32 v206, v192, v201, v203
	v_sub_f32_e32 v192, v192, v206
	v_exp_f32_e32 v192, v192
	s_nop 0
	v_mul_f32_e32 v190, v190, v192
	v_pk_mul_f32 v[106:107], v[106:107], v[192:193] op_sel_hi:[1,0]
	v_pk_mul_f32 v[104:105], v[104:105], v[192:193] op_sel_hi:[1,0]
	v_pk_mul_f32 v[110:111], v[110:111], v[192:193] op_sel_hi:[1,0]
	v_pk_mul_f32 v[108:109], v[108:109], v[192:193] op_sel_hi:[1,0]
	v_pk_mul_f32 v[114:115], v[114:115], v[192:193] op_sel_hi:[1,0]
	v_pk_mul_f32 v[112:113], v[112:113], v[192:193] op_sel_hi:[1,0]
	v_pk_mul_f32 v[122:123], v[122:123], v[192:193] op_sel_hi:[1,0]
	v_pk_mul_f32 v[120:121], v[120:121], v[192:193] op_sel_hi:[1,0]
	v_mov_b64_e32 v[192:193], v[206:207]
	s_branch .LBB0_405

; #define TIDX opaque_tid()
; __device__ __forceinline__ unsigned pk2(float lo, float hi) { const f32x2v v = {lo, hi}; const bf16x2v r = __builtin_convertvector(v, bf16x2v); return __builtin_bit_cast(unsigned, r); }
; __device__ __forceinline__ f32x4 mfma16(bf16x8 a, bf16x8 b, f32x4 c) { return __builtin_amdgcn_mfma_f32_16x16x32_bf16(a, b, c, 0, 0, 0); }
; __device__ __forceinline__ void kv_lwrite(const KVRegs& r, char* lds, int buf) {
;   const int tid = TIDX, row = tid >> 3, cq = tid & 7;
;   char* kt = lds + NSA_KT + buf * 8192 + row * 128;
;   *(u32x4*)(kt + ((cq ^ (row & 7)) << 4)) = r.k0;
;   bf16_t* vt = (bf16_t*)(lds + NSA_VT + buf * 8704) + (cq * 8) * 68 + row;
; #pragma unroll
;   for (int i = 0; i < 4; ++i) { vt[(2 * i) * 68] = (bf16_t)(r.v0[i] & 0xffffu); vt[(2 * i + 1) * 68] = (bf16_t)(r.v0[i] >> 16); }
; }
; template <int MODE>
; __device__ __forceinline__ void nsa_compute(int cur, int buf, int t, int hl, u64 mymask, const bf16x8 (&Qf)[2][2], f32x4 (&O)[4][2], float (&m)[2], float (&l)[2],
;                                             const float (&inv)[2], float* impw, char* lds) {
;     ...
;         float ps = 0.f;
; #pragma unroll
;         for (int kk = 0; kk < 2; ++kk)
; #pragma unroll
;           for (int e = 0; e < 4; ++e) { pv[kk][e] = __builtin_amdgcn_exp2f(sv[kk][e] - me); ps += pv[kk][e]; }
;         l[r] += ps;
;       }
;       if (MODE != 0) {
;         const unsigned w0 = pk2(pv[0][0], pv[0][1]), w1 = pk2(pv[0][2], pv[0][3]), w2 = pk2(pv[1][0], pv[1][1]), w3 = pk2(pv[1][2], pv[1][3]);
;         u32x4 pw; pw.x = w0; pw.y = w1; pw.z = w2; pw.w = w3;
;         Pf[r] = __builtin_bit_cast(bf16x8, pw);
;       }
;     }
;     if (MODE != 0) {
;       bf16x8 vfr[4];
; #pragma unroll
;       for (int df = 0; df < 4; ++df) {
;         const bf16x4 va = *(const bf16x4*)(vt + (df * 16 + fr) * 68 + 32 * s2 + 4 * fq);
;         const bf16x4 vb = *(const bf16x4*)(vt + (df * 16 + fr) * 68 + 32 * s2 + 16 + 4 * fq);
;         bf16x8 vf; vf[0] = va[0]; vf[1] = va[1]; vf[2] = va[2]; vf[3] = va[3]; vf[4] = vb[0]; vf[5] = vb[1]; vf[6] = vb[2]; vf[7] = vb[3];
;         vfr[df] = vf;
;       }
;       __builtin_amdgcn_s_setprio(1);
; #pragma unroll
;       for (int df = 0; df < 4; ++df)
; #pragma unroll
;         for (int r = 0; r < 2; ++r) O[df][r] = mfma16(vfr[df], Pf[r], O[df][r]);
;       __builtin_amdgcn_s_setprio(0);
.LBB0_408:
	v_sub_f32_e32 v119, v199, v118
	v_exp_f32_e32 v175, v119
	v_sub_f32_e32 v119, v198, v118
	v_exp_f32_e32 v198, v119
	v_sub_f32_e32 v119, v173, v118
	v_exp_f32_e32 v173, v119
	v_sub_f32_e32 v119, v172, v118
	v_cvt_pk_bf16_f32 v208, v201, v203
	v_cvt_pk_bf16_f32 v209, v204, v202
	v_cvt_pk_bf16_f32 v210, v205, v200
	v_exp_f32_e32 v172, v119
	v_sub_f32_e32 v119, v240, v118
	ds_read2_b64 v[202:205], v236 offset0:8 offset1:12
	ds_read2_b64 v[240:243], v237 offset0:24 offset1:28
	ds_read2_b64 v[244:247], v238 offset0:40 offset1:44
	ds_read2_b64 v[236:239], v239 offset0:56 offset1:60
	v_exp_f32_e32 v199, v119
	v_sub_f32_e32 v119, v174, v118
	v_sub_f32_e32 v117, v117, v118
	v_sub_f32_e32 v116, v116, v118
	v_exp_f32_e32 v174, v119
	v_exp_f32_e32 v200, v117
	v_exp_f32_e32 v201, v116
	v_cvt_pk_bf16_f32 v211, v207, v206
	v_cvt_pk_bf16_f32 v248, v175, v198
	v_cvt_pk_bf16_f32 v249, v173, v172
	v_cvt_pk_bf16_f32 v250, v199, v174
	v_cvt_pk_bf16_f32 v251, v200, v201
	s_waitcnt lgkmcnt(3)
	v_mfma_f32_16x16x32_bf16 v[116:119], v[202:205], v[208:211], v[104:107]
	v_mfma_f32_16x16x32_bf16 v[104:107], v[202:205], v[248:251], v[124:127]
	s_waitcnt lgkmcnt(2)
	v_mfma_f32_16x16x32_bf16 v[124:127], v[240:243], v[208:211], v[108:111]
	v_mfma_f32_16x16x32_bf16 v[108:111], v[240:243], v[248:251], v[128:131]
	s_waitcnt lgkmcnt(1)
	v_mfma_f32_16x16x32_bf16 v[128:131], v[244:247], v[208:211], v[112:115]
	v_mfma_f32_16x16x32_bf16 v[112:115], v[244:247], v[248:251], v[132:135]
	s_waitcnt lgkmcnt(0)
	v_mfma_f32_16x16x32_bf16 v[132:135], v[236:239], v[208:211], v[120:123]
	v_mfma_f32_16x16x32_bf16 v[120:123], v[236:239], v[248:251], v[168:171]
	s_cmp_lt_i32 s74, 0
	s_cbranch_scc1 .LBB0_410
	s_nop 0
	v_mov_b32 v168, v179
	s_nop 0
	v_ashrrev_i32_e32 v169, 3, v168
	v_xor_b32_e32 v171, v169, v168
	v_lshlrev_b32_e32 v168, 3, v168
	v_lshlrev_b32_e32 v171, 4, v171
	v_and_b32_e32 v168, 56, v168
	v_lshlrev_b32_e32 v170, 7, v169
	v_and_b32_e32 v171, 0x70, v171
	v_mul_u32_u24_e32 v168, 0x88, v168
	v_lshlrev_b32_e32 v169, 1, v169
	v_add3_u32 v170, s71, v170, v171
	v_add3_u32 v168, s72, v168, v169
	s_waitcnt vmcnt(1)
	ds_write_b128 v170, v[48:51]
	s_waitcnt vmcnt(0)
	ds_write_b16 v168, v52 offset:16384
	ds_write_b16_d16_hi v168, v52 offset:16520
	ds_write_b16 v168, v53 offset:16656
	ds_write_b16_d16_hi v168, v53 offset:16792
	ds_write_b16 v168, v54 offset:16928
	ds_write_b16_d16_hi v168, v54 offset:17064
	ds_write_b16 v168, v55 offset:17200
	ds_write_b16_d16_hi v168, v55 offset:17336

; __device__ __forceinline__ f32x4 mfma16(bf16x8 a, bf16x8 b, f32x4 c) { return __builtin_amdgcn_mfma_f32_16x16x32_bf16(a, b, c, 0, 0, 0); }
; template <int MODE>
; __device__ __forceinline__ void nsa_compute(int cur, int buf, int t, int hl, u64 mymask, const bf16x8 (&Qf)[2][2], f32x4 (&O)[4][2], float (&m)[2], float (&l)[2],
;                                             const float (&inv)[2], float* impw, char* lds) {
;     ...
;   const bool selok = (MODE == 2) ? (((mymask >> cur) & 1ull) != 0ull) : true;
;   const float* tb = (MODE == 3) ? (const float*)(lds + NSA_TW) + hl * 640 : (const float*)(lds + NSA_T) + hl * 4160;
;   constexpr int TS = (MODE == 3) ? 640 : 4160;
;   const int base = (MODE <= 1) ? (t - 31 - 16 * (cur * 64 + 4 * fq) + 64) : (t - cur * 64 - 4 * fq + 64);
; #pragma unroll
;   for (int s2 = 0; s2 < 2; ++s2) {
;     f32x4 S[2][2] = {};
;     bf16x8 kfr[2][2];
; #pragma unroll
;     for (int ks = 0; ks < 2; ++ks)
; #pragma unroll
;       for (int kk = 0; kk < 2; ++kk) kfr[ks][kk] = *(const bf16x8*)(kt + (32 * s2 + 16 * kk + fr) * 128 + (((ks * 4 + fq) ^ (fr & 7)) << 4));
;     __builtin_amdgcn_s_setprio(1);
; #pragma unroll
;     for (int ks = 0; ks < 2; ++ks)
; #pragma unroll
;       for (int kk = 0; kk < 2; ++kk)
; #pragma unroll
;         for (int r = 0; r < 2; ++r) S[kk][r] = mfma16(kfr[ks][kk], Qf[r][ks], S[kk][r]);
;     __builtin_amdgcn_s_setprio(0);
;     bf16x8 Pf[2];
;     float g1s[2] = {0.f, 0.f}, p3s[2] = {0.f, 0.f};
; #pragma unroll
;     for (int r = 0; r < 2; ++r) {
;       float sv[2][4];
; #pragma unroll
;       for (int kk = 0; kk < 2; ++kk)
; #pragma unroll
;         for (int e = 0; e < 4; ++e) {
;           const int off = 32 * s2 + 16 * kk + e;
;           int idx;
;           if (MODE <= 1) { idx = base - 16 * off; idx = idx > 0 ? idx : 0; } else idx = base - off;
;           sv[kk][e] = S[kk][r][e] * (0.125f * LOG2E) + tb[r * TS + idx];
;         }
.LBB0_436:
	s_mov_b32 s17, s75
	s_lshl_b64 s[30:31], 1, s17
	v_mov_b32 v74, v179
	v_and_b32_e32 v73, s31, v187
	v_lshrrev_b32_e32 v75, 4, v74
	v_bfe_u32 v80, v74, 4, 2
	v_and_b32_e32 v72, s30, v186
	v_and_b32_e32 v81, 7, v74
	v_and_b32_e32 v94, 15, v74
	s_lshl_b32 s63, s74, 13
	v_cmp_eq_u64_e64 s[36:37], 0, v[72:73]
	v_lshlrev_b32_e32 v95, 2, v80
	v_bitop3_b32 v72, v75, v81, 3 bitop3:0x6c
	v_bitop3_b32 v80, v80, v81, 4 bitop3:0x36
	v_lshlrev_b32_e32 v91, 7, v94
	v_lshl_or_b32 v92, v72, 4, s63
	v_lshl_or_b32 v93, v80, 4, s63
	v_or_b32_e32 v76, v92, v91
	v_or_b32_e32 v84, v93, v91
	ds_read_b128 v[72:75], v76
	ds_read_b128 v[76:79], v76 offset:2048
	ds_read_b128 v[80:83], v84
	ds_read_b128 v[84:87], v84 offset:2048
	s_mov_b32 s75, s46
	v_sub_u32_e32 v251, v180, v95
	v_lshl_add_u32 v251, v251, 2, v181
	s_lshl_b32 s17, s17, 8
	v_subrev_u32_e32 v250, s17, v251
	v_add_u32_e32 v249, 0x8400, v250
	v_add_u32_e32 v248, 0xc500, v250
	ds_read2_b32 v[114:115], v249 offset0:63 offset1:64
	ds_read2_b32 v[116:117], v249 offset0:61 offset1:62
	ds_read2_b32 v[118:119], v249 offset0:47 offset1:48
	ds_read2_b32 v[138:139], v249 offset0:45 offset1:46
	ds_read2_b32 v[140:141], v248 offset0:63 offset1:64
	ds_read2_b32 v[142:143], v248 offset0:61 offset1:62
	ds_read2_b32 v[144:145], v248 offset0:47 offset1:48
	ds_read2_b32 v[148:149], v248 offset0:45 offset1:46
	s_waitcnt lgkmcnt(11)
	v_mfma_f32_16x16x32_bf16 v[96:99], v[72:75], v[0:3], 0
	v_mfma_f32_16x16x32_bf16 v[72:75], v[72:75], v[8:11], 0
	s_waitcnt lgkmcnt(10)
	v_mfma_f32_16x16x32_bf16 v[104:107], v[76:79], v[8:11], 0
	v_mfma_f32_16x16x32_bf16 v[100:103], v[76:79], v[0:3], 0
	s_waitcnt lgkmcnt(9)
	v_mfma_f32_16x16x32_bf16 v[96:99], v[80:83], v[4:7], v[96:99]
	v_mfma_f32_16x16x32_bf16 v[76:79], v[80:83], v[12:15], v[72:75]
	s_waitcnt lgkmcnt(8)
	v_mfma_f32_16x16x32_bf16 v[72:75], v[84:87], v[12:15], v[104:107]
	v_mfma_f32_16x16x32_bf16 v[100:103], v[84:87], v[4:7], v[100:103]
	v_sub_u32_e32 v80, v180, v95
	v_lshl_add_u32 v80, v80, 2, v181
	v_subrev_u32_e32 v90, s17, v80
	s_waitcnt lgkmcnt(7)
	v_fmamk_f32 v87, v96, 0x3e38aa3b, v115
	v_fmamk_f32 v86, v97, 0x3e38aa3b, v114
	s_waitcnt lgkmcnt(6)
	v_fmamk_f32 v83, v98, 0x3e38aa3b, v117
	v_fmamk_f32 v82, v99, 0x3e38aa3b, v116
	s_waitcnt lgkmcnt(5)
	v_fmamk_f32 v81, v100, 0x3e38aa3b, v119
	v_fmamk_f32 v80, v101, 0x3e38aa3b, v118
	s_waitcnt lgkmcnt(4)
	v_fmamk_f32 v97, v102, 0x3e38aa3b, v139
	v_fmamk_f32 v84, v103, 0x3e38aa3b, v138
	v_max3_f32 v85, v87, v86, v83
	v_max3_f32 v88, v82, v81, v80
	v_max_f32_e32 v89, v97, v84
	v_max3_f32 v85, v89, v85, v88
	v_cndmask_b32_e64 v85, v85, v225, s[36:37]
	v_add_f32_e32 v88, 0x41000000, v188
	v_cmp_gt_f32_e32 vcc, v85, v88
	s_cbranch_vccz .LBB0_438
	ds_bpermute_b32 v88, v233, v85
	v_max_f32_e32 v85, v85, v85
	v_mov_b32_e32 v89, v189
	s_waitcnt lgkmcnt(0)
	v_max_f32_e32 v88, v88, v88
	v_max_f32_e32 v85, v85, v88
	ds_bpermute_b32 v88, v234, v85
	s_waitcnt lgkmcnt(0)
	v_max3_f32 v88, v188, v85, v88
	v_sub_f32_e32 v85, v188, v88
	v_exp_f32_e32 v96, v85
	v_mov_b64_e32 v[188:189], v[88:89]
	v_mul_f32_e32 v190, v190, v96
	v_pk_mul_f32 v[18:19], v[18:19], v[96:97] op_sel_hi:[1,0]
	v_pk_mul_f32 v[16:17], v[16:17], v[96:97] op_sel_hi:[1,0]
	v_pk_mul_f32 v[26:27], v[26:27], v[96:97] op_sel_hi:[1,0]
	v_pk_mul_f32 v[24:25], v[24:25], v[96:97] op_sel_hi:[1,0]
	v_pk_mul_f32 v[34:35], v[34:35], v[96:97] op_sel_hi:[1,0]
	v_pk_mul_f32 v[32:33], v[32:33], v[96:97] op_sel_hi:[1,0]
	v_pk_mul_f32 v[42:43], v[42:43], v[96:97] op_sel_hi:[1,0]
	v_pk_mul_f32 v[40:41], v[40:41], v[96:97] op_sel_hi:[1,0]
	s_branch .LBB0_439

; template <int MODE>
; __device__ __forceinline__ void nsa_compute(int cur, int buf, int t, int hl, u64 mymask, const bf16x8 (&Qf)[2][2], f32x4 (&O)[4][2], float (&m)[2], float (&l)[2],
;                                             const float (&inv)[2], float* impw, char* lds) {
;     ...
;     for (int ks = 0; ks < 2; ++ks)
; #pragma unroll
;       for (int kk = 0; kk < 2; ++kk) kfr[ks][kk] = *(const bf16x8*)(kt + (32 * s2 + 16 * kk + fr) * 128 + (((ks * 4 + fq) ^ (fr & 7)) << 4));
;     __builtin_amdgcn_s_setprio(1);
; #pragma unroll
;     for (int ks = 0; ks < 2; ++ks)
; #pragma unroll
;       for (int kk = 0; kk < 2; ++kk)
; #pragma unroll
;         for (int r = 0; r < 2; ++r) S[kk][r] = mfma16(kfr[ks][kk], Qf[r][ks], S[kk][r]);
;     __builtin_amdgcn_s_setprio(0);
;     bf16x8 Pf[2];
;     float g1s[2] = {0.f, 0.f}, p3s[2] = {0.f, 0.f};
; #pragma unroll
;     for (int r = 0; r < 2; ++r) {
;       float sv[2][4];
; #pragma unroll
;       for (int kk = 0; kk < 2; ++kk)
; #pragma unroll
;         for (int e = 0; e < 4; ++e) {
;           const int off = 32 * s2 + 16 * kk + e;
;           int idx;
;           if (MODE <= 1) { idx = base - 16 * off; idx = idx > 0 ? idx : 0; } else idx = base - off;
;     ...
;           for (int e = 0; e < 4; ++e) { pv[kk][e] = __builtin_amdgcn_exp2f(sv[kk][e] - me); ps += pv[kk][e]; }
;         l[r] += ps;
;       }
;       if (MODE != 0) {
;         const unsigned w0 = pk2(pv[0][0], pv[0][1]), w1 = pk2(pv[0][2], pv[0][3]), w2 = pk2(pv[1][0], pv[1][1]), w3 = pk2(pv[1][2], pv[1][3]);
;         u32x4 pw; pw.x = w0; pw.y = w1; pw.z = w2; pw.w = w3;
;         Pf[r] = __builtin_bit_cast(bf16x8, pw);
;       }
;     }
;     if (MODE != 0) {
;       bf16x8 vfr[4];
; #pragma unroll
;       for (int df = 0; df < 4; ++df) {
;         const bf16x4 va = *(const bf16x4*)(vt + (df * 16 + fr) * 68 + 32 * s2 + 4 * fq);
;         const bf16x4 vb = *(const bf16x4*)(vt + (df * 16 + fr) * 68 + 32 * s2 + 16 + 4 * fq);
;         bf16x8 vf; vf[0] = va[0]; vf[1] = va[1]; vf[2] = va[2]; vf[3] = va[3]; vf[4] = vb[0]; vf[5] = vb[1]; vf[6] = vb[2]; vf[7] = vb[3];
;         vfr[df] = vf;
;       }
;       __builtin_amdgcn_s_setprio(1);
; #pragma unroll
;       for (int df = 0; df < 4; ++df)
; #pragma unroll
;         for (int r = 0; r < 2; ++r) O[df][r] = mfma16(vfr[df], Pf[r], O[df][r]);
;       __builtin_amdgcn_s_setprio(0);
.LBB0_442:
	v_cndmask_b32_e64 v74, v74, v228, s[36:37]
	v_sub_f32_e32 v75, v81, v74
	v_exp_f32_e32 v75, v75
	v_sub_f32_e32 v80, v80, v74
	v_exp_f32_e32 v80, v80
	v_sub_f32_e32 v78, v78, v74
	v_exp_f32_e32 v78, v78
	v_sub_f32_e32 v81, v82, v74
	v_exp_f32_e32 v81, v81
	v_sub_f32_e32 v77, v77, v74
	v_add_f32_e32 v79, 0, v75
	v_exp_f32_e32 v77, v77
	v_sub_f32_e32 v76, v76, v74
	v_add_f32_e32 v79, v80, v79
	v_exp_f32_e32 v76, v76
	v_sub_f32_e32 v73, v73, v74
	v_add_f32_e32 v79, v78, v79
	v_exp_f32_e32 v73, v73
	v_sub_f32_e32 v72, v72, v74
	v_add_f32_e32 v79, v81, v79
	v_exp_f32_e32 v72, v72
	v_add_f32_e32 v79, v77, v79
	v_add_f32_e32 v79, v76, v79
	v_add_f32_e32 v79, v73, v79
	s_lshl_b32 s17, s74, 9
	v_add_f32_e32 v74, v72, v79
	v_cvt_pk_bf16_f32 v101, v73, v72
	v_mul_u32_u24_e32 v72, 0x44, v94
	s_add_i32 s71, s63, s17
	v_lshlrev_b32_e32 v72, 1, v72
	v_lshlrev_b32_e32 v73, 1, v95
	v_add3_u32 v72, s71, v72, v73
	v_add_u32_e32 v94, 0x4000, v72
	v_cvt_pk_bf16_f32 v87, v87, v88
	v_cvt_pk_bf16_f32 v88, v89, v96
	v_cvt_pk_bf16_f32 v89, v97, v84
	v_cvt_pk_bf16_f32 v99, v78, v81
	v_cvt_pk_bf16_f32 v100, v77, v76
	ds_read2_b64 v[76:79], v94 offset1:4
	v_add_u32_e32 v95, 0x4800, v72
	v_add_u32_e32 v96, 0x5000, v72
	v_add_u32_e32 v97, 0x5800, v72
	ds_read2_b64 v[102:105], v95 offset0:16 offset1:20
	ds_read2_b64 v[106:109], v96 offset0:32 offset1:36
	ds_read2_b64 v[110:113], v97 offset0:48 offset1:52
	v_cvt_pk_bf16_f32 v86, v85, v86
	v_add_f32_e32 v191, v191, v74
	v_cvt_pk_bf16_f32 v98, v75, v80
	s_waitcnt lgkmcnt(3)
	v_mfma_f32_16x16x32_bf16 v[72:75], v[76:79], v[86:89], v[16:19]
	v_mfma_f32_16x16x32_bf16 v[80:83], v[76:79], v[98:101], v[20:23]
	s_waitcnt lgkmcnt(2)
	v_mfma_f32_16x16x32_bf16 v[24:27], v[102:105], v[86:89], v[24:27]
	v_mfma_f32_16x16x32_bf16 v[76:79], v[102:105], v[98:101], v[28:31]
	s_waitcnt lgkmcnt(1)
	v_mfma_f32_16x16x32_bf16 v[20:23], v[106:109], v[86:89], v[32:35]
	v_mfma_f32_16x16x32_bf16 v[32:35], v[106:109], v[98:101], v[36:39]
	s_waitcnt lgkmcnt(0)
	v_mfma_f32_16x16x32_bf16 v[16:19], v[110:113], v[86:89], v[40:43]
	v_mfma_f32_16x16x32_bf16 v[28:31], v[110:113], v[98:101], v[44:47]
	s_nop 0
	s_nop 0
	v_add_u32_e32 v40, v92, v91
	v_add_u32_e32 v84, v93, v91
	ds_read_b128 v[36:39], v40 offset:4096
	ds_read_b128 v[40:43], v40 offset:6144
	ds_read_b128 v[44:47], v84 offset:4096
	ds_read_b128 v[84:87], v84 offset:6144
	v_add_u32_e32 v251, 0x8400, v90
	v_add_u32_e32 v250, 0xc500, v90
	ds_read2_b32 v[138:139], v251 offset0:31 offset1:32
	ds_read2_b32 v[140:141], v251 offset0:29 offset1:30
	ds_read2_b32 v[142:143], v251 offset0:15 offset1:16
	ds_read2_b32 v[148:149], v251 offset0:13 offset1:14
	ds_read2_b32 v[150:151], v250 offset0:31 offset1:32
	ds_read2_b32 v[152:153], v250 offset0:29 offset1:30
	ds_read2_b32 v[154:155], v250 offset0:15 offset1:16
	ds_read2_b32 v[156:157], v250 offset0:13 offset1:14
	s_waitcnt lgkmcnt(11)
	v_mfma_f32_16x16x32_bf16 v[98:101], v[36:39], v[0:3], 0
	v_mfma_f32_16x16x32_bf16 v[36:39], v[36:39], v[8:11], 0
	s_waitcnt lgkmcnt(10)
	v_mfma_f32_16x16x32_bf16 v[106:109], v[40:43], v[8:11], 0
	v_mfma_f32_16x16x32_bf16 v[102:105], v[40:43], v[0:3], 0
	s_waitcnt lgkmcnt(9)
	v_mfma_f32_16x16x32_bf16 v[40:43], v[44:47], v[12:15], v[36:39]
	s_waitcnt lgkmcnt(8)
	v_mfma_f32_16x16x32_bf16 v[36:39], v[84:87], v[12:15], v[106:109]
	v_mfma_f32_16x16x32_bf16 v[98:101], v[44:47], v[4:7], v[98:101]
	v_mfma_f32_16x16x32_bf16 v[102:105], v[84:87], v[4:7], v[102:105]
	s_waitcnt lgkmcnt(7)
	s_nop 4
	s_nop 0
	v_fmamk_f32 v91, v98, 0x3e38aa3b, v139
	v_fmamk_f32 v84, v99, 0x3e38aa3b, v138
	s_waitcnt lgkmcnt(6)
	v_fmamk_f32 v85, v100, 0x3e38aa3b, v141
	v_fmamk_f32 v46, v101, 0x3e38aa3b, v140
	s_waitcnt lgkmcnt(5)
	v_fmamk_f32 v45, v102, 0x3e38aa3b, v143
	v_fmamk_f32 v44, v103, 0x3e38aa3b, v142
	v_max3_f32 v47, v91, v84, v85
	s_waitcnt lgkmcnt(4)
	v_fmamk_f32 v92, v104, 0x3e38aa3b, v149
	v_fmamk_f32 v86, v105, 0x3e38aa3b, v148
	v_max3_f32 v87, v46, v45, v44
	v_max_f32_e32 v88, v92, v86
	v_max3_f32 v47, v88, v47, v87
	v_cndmask_b32_e64 v47, v47, v225, s[36:37]
	v_add_f32_e32 v87, 0x41000000, v188
	v_cmp_gt_f32_e32 vcc, v47, v87
	s_cbranch_vccz .LBB0_444
	ds_bpermute_b32 v87, v233, v47
	v_max_f32_e32 v47, v47, v47
	v_mov_b32_e32 v89, v189
	s_waitcnt lgkmcnt(0)
	v_max_f32_e32 v87, v87, v87
	v_max_f32_e32 v47, v47, v87
	ds_bpermute_b32 v87, v234, v47
	s_waitcnt lgkmcnt(0)
	v_max3_f32 v88, v188, v47, v87
	v_sub_f32_e32 v47, v188, v88
	v_exp_f32_e32 v98, v47
	v_mov_b64_e32 v[188:189], v[88:89]
	v_mul_f32_e32 v190, v190, v98
	v_pk_mul_f32 v[74:75], v[74:75], v[98:99] op_sel_hi:[1,0]
	v_pk_mul_f32 v[72:73], v[72:73], v[98:99] op_sel_hi:[1,0]
	v_pk_mul_f32 v[26:27], v[26:27], v[98:99] op_sel_hi:[1,0]
	v_pk_mul_f32 v[24:25], v[24:25], v[98:99] op_sel_hi:[1,0]
	v_pk_mul_f32 v[22:23], v[22:23], v[98:99] op_sel_hi:[1,0]
	v_pk_mul_f32 v[20:21], v[20:21], v[98:99] op_sel_hi:[1,0]
	v_pk_mul_f32 v[18:19], v[18:19], v[98:99] op_sel_hi:[1,0]
	v_pk_mul_f32 v[16:17], v[16:17], v[98:99] op_sel_hi:[1,0]
	s_branch .LBB0_445

; #define TIDX opaque_tid()
; __device__ __forceinline__ unsigned pk2(float lo, float hi) { const f32x2v v = {lo, hi}; const bf16x2v r = __builtin_convertvector(v, bf16x2v); return __builtin_bit_cast(unsigned, r); }
; __device__ __forceinline__ void kv_lwrite(const KVRegs& r, char* lds, int buf) {
;   const int tid = TIDX, row = tid >> 3, cq = tid & 7;
;   char* kt = lds + NSA_KT + buf * 8192 + row * 128;
;   *(u32x4*)(kt + ((cq ^ (row & 7)) << 4)) = r.k0;
;   bf16_t* vt = (bf16_t*)(lds + NSA_VT + buf * 8704) + (cq * 8) * 68 + row;
; #pragma unroll
;   for (int i = 0; i < 4; ++i) { vt[(2 * i) * 68] = (bf16_t)(r.v0[i] & 0xffffu); vt[(2 * i + 1) * 68] = (bf16_t)(r.v0[i] >> 16); }
; }
; template <int MODE>
; __device__ __forceinline__ void nsa_compute(int cur, int buf, int t, int hl, u64 mymask, const bf16x8 (&Qf)[2][2], f32x4 (&O)[4][2], float (&m)[2], float (&l)[2],
;                                             const float (&inv)[2], float* impw, char* lds) {
;     ...
;         const float me = (MODE == 2) ? (selok ? m[r] : __builtin_inff()) : m[r];
;         float ps = 0.f;
; #pragma unroll
;         for (int kk = 0; kk < 2; ++kk)
; #pragma unroll
;           for (int e = 0; e < 4; ++e) { pv[kk][e] = __builtin_amdgcn_exp2f(sv[kk][e] - me); ps += pv[kk][e]; }
;         l[r] += ps;
;       }
;       if (MODE != 0) {
;         const unsigned w0 = pk2(pv[0][0], pv[0][1]), w1 = pk2(pv[0][2], pv[0][3]), w2 = pk2(pv[1][0], pv[1][1]), w3 = pk2(pv[1][2], pv[1][3]);
;         u32x4 pw; pw.x = w0; pw.y = w1; pw.z = w2; pw.w = w3;
;         Pf[r] = __builtin_bit_cast(bf16x8, pw);
;       }
;     }
;     if (MODE != 0) {
;       bf16x8 vfr[4];
; #pragma unroll
;       for (int df = 0; df < 4; ++df) {
;         const bf16x4 va = *(const bf16x4*)(vt + (df * 16 + fr) * 68 + 32 * s2 + 4 * fq);
;         const bf16x4 vb = *(const bf16x4*)(vt + (df * 16 + fr) * 68 + 32 * s2 + 16 + 4 * fq);
;         bf16x8 vf; vf[0] = va[0]; vf[1] = va[1]; vf[2] = va[2]; vf[3] = va[3]; vf[4] = vb[0]; vf[5] = vb[1]; vf[6] = vb[2]; vf[7] = vb[3];
;         vfr[df] = vf;
;       }
;       __builtin_amdgcn_s_setprio(1);
; #pragma unroll
;       for (int df = 0; df < 4; ++df)
; #pragma unroll
;         for (int r = 0; r < 2; ++r) O[df][r] = mfma16(vfr[df], Pf[r], O[df][r]);
;       __builtin_amdgcn_s_setprio(0);
.LBB0_448:
	v_cndmask_b32_e64 v91, v37, v228, s[36:37]
	v_cvt_pk_bf16_f32 v104, v47, v84
	v_cvt_pk_bf16_f32 v105, v85, v46
	v_cvt_pk_bf16_f32 v106, v87, v88
	v_cvt_pk_bf16_f32 v107, v89, v86
	v_sub_f32_e32 v37, v45, v91
	v_sub_f32_e32 v38, v44, v91
	ds_read2_b64 v[44:47], v94 offset0:8 offset1:12
	ds_read2_b64 v[84:87], v95 offset0:24 offset1:28
	ds_read2_b64 v[108:111], v96 offset0:40 offset1:44
	ds_read2_b64 v[112:115], v97 offset0:56 offset1:60
	v_sub_f32_e32 v39, v41, v91
	v_sub_f32_e32 v40, v40, v91
	v_sub_f32_e32 v41, v43, v91
	v_sub_f32_e32 v42, v42, v91
	v_sub_f32_e32 v43, v90, v91
	v_sub_f32_e32 v36, v36, v91
	v_exp_f32_e32 v37, v37
	v_exp_f32_e32 v38, v38
	v_exp_f32_e32 v39, v39
	v_exp_f32_e32 v40, v40
	v_exp_f32_e32 v41, v41
	v_exp_f32_e32 v42, v42
	v_exp_f32_e32 v43, v43
	v_exp_f32_e32 v36, v36
	v_cvt_pk_bf16_f32 v116, v37, v38
	v_cvt_pk_bf16_f32 v117, v39, v40
	v_cvt_pk_bf16_f32 v118, v41, v42
	v_cvt_pk_bf16_f32 v119, v43, v36
	s_waitcnt lgkmcnt(3)
	v_mfma_f32_16x16x32_bf16 v[88:91], v[44:47], v[104:107], v[72:75]
	v_mfma_f32_16x16x32_bf16 v[96:99], v[44:47], v[116:119], v[80:83]
	s_waitcnt lgkmcnt(2)
	v_mfma_f32_16x16x32_bf16 v[100:103], v[84:87], v[104:107], v[24:27]
	v_mfma_f32_16x16x32_bf16 v[84:87], v[84:87], v[116:119], v[76:79]
	s_waitcnt lgkmcnt(1)
	v_mfma_f32_16x16x32_bf16 v[92:95], v[108:111], v[104:107], v[20:23]
	v_mfma_f32_16x16x32_bf16 v[76:79], v[108:111], v[116:119], v[32:35]
	s_waitcnt lgkmcnt(0)
	v_mfma_f32_16x16x32_bf16 v[80:83], v[112:115], v[104:107], v[16:19]
	v_mfma_f32_16x16x32_bf16 v[72:75], v[112:115], v[116:119], v[28:31]
	s_xor_b32 s74, s74, 1
	s_cmp_lt_i32 s16, 0
	s_cbranch_scc1 .LBB0_450
	v_mov_b32 v16, v179
	s_lshl_b32 s17, s74, 13
	v_ashrrev_i32_e32 v17, 3, v16
	v_xor_b32_e32 v19, v17, v16
	v_lshl_add_u32 v18, v17, 7, s17
	v_lshlrev_b32_e32 v19, 4, v19
	s_movk_i32 s30, 0x70
	v_lshlrev_b32_e32 v16, 3, v16
	v_and_or_b32 v18, v19, s30, v18
	s_lshl_b32 s30, s74, 9
	v_and_b32_e32 v16, 56, v16
	s_add_i32 s17, s17, s30
	v_mul_u32_u24_e32 v16, 0x88, v16
	v_lshlrev_b32_e32 v17, 1, v17
	v_add3_u32 v16, s17, v16, v17
	s_waitcnt vmcnt(1)
	ds_write_b128 v18, v[56:59]
	s_waitcnt vmcnt(0)
	ds_write_b16 v16, v60 offset:16384
	ds_write_b16_d16_hi v16, v60 offset:16520
	ds_write_b16 v16, v61 offset:16656
	ds_write_b16_d16_hi v16, v61 offset:16792
	ds_write_b16 v16, v62 offset:16928
	ds_write_b16_d16_hi v16, v62 offset:17064
	ds_write_b16 v16, v63 offset:17200
	ds_write_b16_d16_hi v16, v63 offset:17336

; __device__ __forceinline__ f32x4 mfma16(bf16x8 a, bf16x8 b, f32x4 c) { return __builtin_amdgcn_mfma_f32_16x16x32_bf16(a, b, c, 0, 0, 0); }
; template <int MODE>
; __device__ __forceinline__ void nsa_compute(int cur, int buf, int t, int hl, u64 mymask, const bf16x8 (&Qf)[2][2], f32x4 (&O)[4][2], float (&m)[2], float (&l)[2],
;                                             const float (&inv)[2], float* impw, char* lds) {
;     ...
;   const bool selok = (MODE == 2) ? (((mymask >> cur) & 1ull) != 0ull) : true;
;   const float* tb = (MODE == 3) ? (const float*)(lds + NSA_TW) + hl * 640 : (const float*)(lds + NSA_T) + hl * 4160;
;   constexpr int TS = (MODE == 3) ? 640 : 4160;
;   const int base = (MODE <= 1) ? (t - 31 - 16 * (cur * 64 + 4 * fq) + 64) : (t - cur * 64 - 4 * fq + 64);
; #pragma unroll
;   for (int s2 = 0; s2 < 2; ++s2) {
;     f32x4 S[2][2] = {};
;     bf16x8 kfr[2][2];
; #pragma unroll
;     for (int ks = 0; ks < 2; ++ks)
; #pragma unroll
;       for (int kk = 0; kk < 2; ++kk) kfr[ks][kk] = *(const bf16x8*)(kt + (32 * s2 + 16 * kk + fr) * 128 + (((ks * 4 + fq) ^ (fr & 7)) << 4));
;     __builtin_amdgcn_s_setprio(1);
; #pragma unroll
;     for (int ks = 0; ks < 2; ++ks)
; #pragma unroll
;       for (int kk = 0; kk < 2; ++kk)
; #pragma unroll
;         for (int r = 0; r < 2; ++r) S[kk][r] = mfma16(kfr[ks][kk], Qf[r][ks], S[kk][r]);
;     __builtin_amdgcn_s_setprio(0);
;     bf16x8 Pf[2];
;     float g1s[2] = {0.f, 0.f}, p3s[2] = {0.f, 0.f};
; #pragma unroll
;     for (int r = 0; r < 2; ++r) {
;       float sv[2][4];
; #pragma unroll
;       for (int kk = 0; kk < 2; ++kk)
; #pragma unroll
;         for (int e = 0; e < 4; ++e) {
;           const int off = 32 * s2 + 16 * kk + e;
;           int idx;
;           if (MODE <= 1) { idx = base - 16 * off; idx = idx > 0 ? idx : 0; } else idx = base - off;
;           sv[kk][e] = S[kk][r][e] * (0.125f * LOG2E) + tb[r * TS + idx];
;         }
;     ...
;         float ps = 0.f;
; #pragma unroll
;         for (int kk = 0; kk < 2; ++kk)
; #pragma unroll
;           for (int e = 0; e < 4; ++e) { pv[kk][e] = __builtin_amdgcn_exp2f(sv[kk][e] - me); ps += pv[kk][e]; }
;         l[r] += ps;
.LBB0_452:
	v_add_f32_e32 v16, 0, v37
	v_add_f32_e32 v16, v38, v16
	v_add_f32_e32 v16, v39, v16
	v_add_f32_e32 v16, v40, v16
	v_add_f32_e32 v16, v41, v16
	v_add_f32_e32 v16, v42, v16
	v_add_f32_e32 v16, v43, v16
	v_add_f32_e32 v16, v36, v16
	s_cmp_lt_i32 s16, 0
	v_add_f32_e32 v145, v145, v16
	s_cbranch_scc1 .LBB0_435
	s_lshl_b64 s[30:31], 1, s16
	v_mov_b32 v18, v179
	v_and_b32_e32 v17, s31, v187
	v_lshrrev_b32_e32 v19, 4, v18
	v_bfe_u32 v24, v18, 4, 2
	v_and_b32_e32 v16, s30, v186
	v_and_b32_e32 v25, 7, v18
	v_and_b32_e32 v117, 15, v18
	s_lshl_b32 s72, s74, 13
	v_cmp_eq_u64_e64 s[36:37], 0, v[16:17]
	v_lshlrev_b32_e32 v118, 2, v24
	v_bitop3_b32 v16, v19, v25, 3 bitop3:0x6c
	v_bitop3_b32 v24, v24, v25, 4 bitop3:0x36
	v_lshlrev_b32_e32 v114, 7, v117
	v_lshl_or_b32 v115, v16, 4, s72
	v_lshl_or_b32 v116, v24, 4, s72
	v_or_b32_e32 v20, v115, v114
	v_or_b32_e32 v28, v116, v114
	ds_read_b128 v[16:19], v20
	ds_read_b128 v[20:23], v20 offset:2048
	ds_read_b128 v[24:27], v28
	ds_read_b128 v[28:31], v28 offset:2048
	v_sub_u32_e32 v251, v180, v118
	v_lshl_add_u32 v251, v251, 2, v181
	s_lshl_b32 s16, s16, 8
	v_subrev_u32_e32 v250, s16, v251
	v_add_u32_e32 v249, 0x8400, v250
	v_add_u32_e32 v248, 0xc500, v250
	ds_read2_b32 v[148:149], v249 offset0:63 offset1:64
	ds_read2_b32 v[150:151], v249 offset0:61 offset1:62
	ds_read2_b32 v[152:153], v249 offset0:47 offset1:48
	ds_read2_b32 v[154:155], v249 offset0:45 offset1:46
	ds_read2_b32 v[156:157], v248 offset0:63 offset1:64
	ds_read2_b32 v[168:169], v248 offset0:61 offset1:62
	ds_read2_b32 v[170:171], v248 offset0:47 offset1:48
	ds_read2_b32 v[172:173], v248 offset0:45 offset1:46
	s_waitcnt lgkmcnt(11)
	v_mfma_f32_16x16x32_bf16 v[32:35], v[16:19], v[0:3], 0
	v_mfma_f32_16x16x32_bf16 v[16:19], v[16:19], v[8:11], 0
	s_waitcnt lgkmcnt(10)
	v_mfma_f32_16x16x32_bf16 v[40:43], v[20:23], v[0:3], 0
	v_mfma_f32_16x16x32_bf16 v[20:23], v[20:23], v[8:11], 0
	s_waitcnt lgkmcnt(9)
	v_mfma_f32_16x16x32_bf16 v[36:39], v[24:27], v[12:15], v[16:19]
	s_waitcnt lgkmcnt(8)
	v_mfma_f32_16x16x32_bf16 v[16:19], v[28:31], v[4:7], v[40:43]
	v_mfma_f32_16x16x32_bf16 v[28:31], v[28:31], v[12:15], v[20:23]
	v_mfma_f32_16x16x32_bf16 v[32:35], v[24:27], v[4:7], v[32:35]
	s_nop 0
	s_nop 0
	v_sub_u32_e32 v20, v180, v118
	v_lshl_add_u32 v20, v20, 2, v181
	v_subrev_u32_e32 v122, s16, v20
	s_waitcnt lgkmcnt(7)
	s_nop 1
	v_fmamk_f32 v47, v32, 0x3e38aa3b, v149
	v_fmamk_f32 v46, v33, 0x3e38aa3b, v148
	s_waitcnt lgkmcnt(6)
	v_fmamk_f32 v43, v34, 0x3e38aa3b, v151
	v_fmamk_f32 v42, v35, 0x3e38aa3b, v150
	s_waitcnt lgkmcnt(5)
	v_fmamk_f32 v41, v16, 0x3e38aa3b, v153
	v_fmamk_f32 v40, v17, 0x3e38aa3b, v152
	v_max3_f32 v16, v47, v46, v43
	v_max3_f32 v17, v42, v41, v40
	s_waitcnt lgkmcnt(4)
	v_fmamk_f32 v45, v18, 0x3e38aa3b, v155
	v_fmamk_f32 v44, v19, 0x3e38aa3b, v154
	v_max_f32_e32 v18, v45, v44
	v_max3_f32 v16, v18, v16, v17
	v_cndmask_b32_e64 v16, v16, v225, s[36:37]
	v_add_f32_e32 v17, 0x41000000, v188
	v_cmp_gt_f32_e32 vcc, v16, v17
	s_cbranch_vccz .LBB0_455
	ds_bpermute_b32 v17, v233, v16
	v_max_f32_e32 v16, v16, v16
	v_mov_b32_e32 v105, v189
	v_mov_b32_e32 v147, v145
	s_waitcnt lgkmcnt(0)
	v_max_f32_e32 v17, v17, v17
	v_max_f32_e32 v16, v16, v17
	ds_bpermute_b32 v17, v234, v16
	s_waitcnt lgkmcnt(0)
	v_max3_f32 v104, v188, v16, v17
	v_sub_f32_e32 v16, v188, v104
	v_exp_f32_e32 v32, v16
	v_mov_b64_e32 v[188:189], v[104:105]
	v_mul_f32_e32 v146, v144, v32
	v_pk_mul_f32 v[26:27], v[90:91], v[32:33] op_sel_hi:[1,0]
	v_pk_mul_f32 v[24:25], v[88:89], v[32:33] op_sel_hi:[1,0]
	v_pk_mul_f32 v[18:19], v[102:103], v[32:33] op_sel_hi:[1,0]
	v_pk_mul_f32 v[16:17], v[100:101], v[32:33] op_sel_hi:[1,0]
	v_pk_mul_f32 v[22:23], v[94:95], v[32:33] op_sel_hi:[1,0]
	v_pk_mul_f32 v[20:21], v[92:93], v[32:33] op_sel_hi:[1,0]
	v_pk_mul_f32 v[34:35], v[82:83], v[32:33] op_sel_hi:[1,0]
	v_pk_mul_f32 v[32:33], v[80:81], v[32:33] op_sel_hi:[1,0]
	s_branch .LBB0_456

; template <int MODE>
; __device__ __forceinline__ void nsa_compute(int cur, int buf, int t, int hl, u64 mymask, const bf16x8 (&Qf)[2][2], f32x4 (&O)[4][2], float (&m)[2], float (&l)[2],
;                                             const float (&inv)[2], float* impw, char* lds) {
;     ...
;     for (int ks = 0; ks < 2; ++ks)
; #pragma unroll
;       for (int kk = 0; kk < 2; ++kk) kfr[ks][kk] = *(const bf16x8*)(kt + (32 * s2 + 16 * kk + fr) * 128 + (((ks * 4 + fq) ^ (fr & 7)) << 4));
;     __builtin_amdgcn_s_setprio(1);
; #pragma unroll
;     for (int ks = 0; ks < 2; ++ks)
; #pragma unroll
;       for (int kk = 0; kk < 2; ++kk)
; #pragma unroll
;         for (int r = 0; r < 2; ++r) S[kk][r] = mfma16(kfr[ks][kk], Qf[r][ks], S[kk][r]);
;     __builtin_amdgcn_s_setprio(0);
;     bf16x8 Pf[2];
;     float g1s[2] = {0.f, 0.f}, p3s[2] = {0.f, 0.f};
; #pragma unroll
;     for (int r = 0; r < 2; ++r) {
;       float sv[2][4];
; #pragma unroll
;       for (int kk = 0; kk < 2; ++kk)
; #pragma unroll
;         for (int e = 0; e < 4; ++e) {
;           const int off = 32 * s2 + 16 * kk + e;
;           int idx;
;           if (MODE <= 1) { idx = base - 16 * off; idx = idx > 0 ? idx : 0; } else idx = base - off;
;     ...
;           for (int e = 0; e < 4; ++e) { pv[kk][e] = __builtin_amdgcn_exp2f(sv[kk][e] - me); ps += pv[kk][e]; }
;         l[r] += ps;
;       }
;       if (MODE != 0) {
;         const unsigned w0 = pk2(pv[0][0], pv[0][1]), w1 = pk2(pv[0][2], pv[0][3]), w2 = pk2(pv[1][0], pv[1][1]), w3 = pk2(pv[1][2], pv[1][3]);
;         u32x4 pw; pw.x = w0; pw.y = w1; pw.z = w2; pw.w = w3;
;         Pf[r] = __builtin_bit_cast(bf16x8, pw);
;       }
;     }
;     if (MODE != 0) {
;       bf16x8 vfr[4];
; #pragma unroll
;       for (int df = 0; df < 4; ++df) {
;         const bf16x4 va = *(const bf16x4*)(vt + (df * 16 + fr) * 68 + 32 * s2 + 4 * fq);
;         const bf16x4 vb = *(const bf16x4*)(vt + (df * 16 + fr) * 68 + 32 * s2 + 16 + 4 * fq);
;         bf16x8 vf; vf[0] = va[0]; vf[1] = va[1]; vf[2] = va[2]; vf[3] = va[3]; vf[4] = vb[0]; vf[5] = vb[1]; vf[6] = vb[2]; vf[7] = vb[3];
;         vfr[df] = vf;
;       }
;       __builtin_amdgcn_s_setprio(1);
; #pragma unroll
;       for (int df = 0; df < 4; ++df)
; #pragma unroll
;         for (int r = 0; r < 2; ++r) O[df][r] = mfma16(vfr[df], Pf[r], O[df][r]);
;       __builtin_amdgcn_s_setprio(0);
.LBB0_459:
	v_cndmask_b32_e64 v30, v30, v228, s[36:37]
	v_sub_f32_e32 v31, v47, v30
	v_exp_f32_e32 v31, v31
	v_sub_f32_e32 v46, v46, v30
	v_exp_f32_e32 v46, v46
	v_sub_f32_e32 v113, v113, v30
	v_exp_f32_e32 v113, v113
	v_sub_f32_e32 v112, v112, v30
	v_exp_f32_e32 v112, v112
	v_sub_f32_e32 v45, v45, v30
	v_add_f32_e32 v47, 0, v31
	v_exp_f32_e32 v45, v45
	v_sub_f32_e32 v44, v44, v30
	v_add_f32_e32 v47, v46, v47
	v_exp_f32_e32 v44, v44
	v_sub_f32_e32 v29, v29, v30
	v_add_f32_e32 v47, v113, v47
	v_exp_f32_e32 v29, v29
	v_sub_f32_e32 v28, v28, v30
	v_add_f32_e32 v47, v112, v47
	v_exp_f32_e32 v28, v28
	v_add_f32_e32 v47, v45, v47
	v_add_f32_e32 v47, v44, v47
	v_add_f32_e32 v47, v29, v47
	s_lshl_b32 s16, s74, 9
	v_add_f32_e32 v30, v28, v47
	v_cvt_pk_bf16_f32 v135, v29, v28
	v_mul_u32_u24_e32 v28, 0x44, v117
	s_add_i32 s73, s72, s16
	v_lshlrev_b32_e32 v28, 1, v28
	v_lshlrev_b32_e32 v29, 1, v118
	v_add3_u32 v28, s73, v28, v29
	v_cvt_pk_bf16_f32 v129, v121, v123
	v_cvt_pk_bf16_f32 v130, v124, v125
	v_add_u32_e32 v123, 0x4000, v28
	v_add_u32_e32 v124, 0x4800, v28
	v_cvt_pk_bf16_f32 v128, v119, v120
	v_cvt_pk_bf16_f32 v131, v126, v127
	v_cvt_pk_bf16_f32 v132, v31, v46
	v_cvt_pk_bf16_f32 v134, v45, v44
	ds_read2_b64 v[44:47], v123 offset1:4
	ds_read2_b64 v[118:121], v124 offset0:16 offset1:20
	v_add_u32_e32 v125, 0x5000, v28
	v_add_u32_e32 v126, 0x5800, v28
	ds_read2_b64 v[136:139], v125 offset0:32 offset1:36
	ds_read2_b64 v[140:143], v126 offset0:48 offset1:52
	v_add_f32_e32 v147, v147, v30
	v_cvt_pk_bf16_f32 v133, v113, v112
	s_waitcnt lgkmcnt(3)
	v_mfma_f32_16x16x32_bf16 v[28:31], v[44:47], v[128:131], v[24:27]
	v_mfma_f32_16x16x32_bf16 v[44:47], v[44:47], v[132:135], v[36:39]
	s_waitcnt lgkmcnt(2)
	v_mfma_f32_16x16x32_bf16 v[24:27], v[118:121], v[128:131], v[16:19]
	v_mfma_f32_16x16x32_bf16 v[40:43], v[118:121], v[132:135], v[40:43]
	s_waitcnt lgkmcnt(1)
	v_mfma_f32_16x16x32_bf16 v[20:23], v[136:139], v[128:131], v[20:23]
	v_mfma_f32_16x16x32_bf16 v[36:39], v[136:139], v[132:135], v[104:107]
	s_waitcnt lgkmcnt(0)
	v_mfma_f32_16x16x32_bf16 v[16:19], v[140:143], v[128:131], v[32:35]
	v_mfma_f32_16x16x32_bf16 v[32:35], v[140:143], v[132:135], v[108:111]
	s_nop 1
	s_nop 0
	v_add_u32_e32 v108, v115, v114
	v_add_u32_e32 v116, v116, v114
	ds_read_b128 v[104:107], v108 offset:4096
	ds_read_b128 v[108:111], v108 offset:6144
	ds_read_b128 v[112:115], v116 offset:4096
	ds_read_b128 v[116:119], v116 offset:6144
	v_add_u32_e32 v251, 0x8400, v122
	v_add_u32_e32 v250, 0xc500, v122
	ds_read2_b32 v[152:153], v251 offset0:31 offset1:32
	ds_read2_b32 v[154:155], v251 offset0:29 offset1:30
	ds_read2_b32 v[156:157], v251 offset0:15 offset1:16
	ds_read2_b32 v[168:169], v251 offset0:13 offset1:14
	ds_read2_b32 v[170:171], v250 offset0:31 offset1:32
	ds_read2_b32 v[172:173], v250 offset0:29 offset1:30
	ds_read2_b32 v[174:175], v250 offset0:15 offset1:16
	ds_read2_b32 v[192:193], v250 offset0:13 offset1:14
	s_waitcnt lgkmcnt(11)
	v_mfma_f32_16x16x32_bf16 v[128:131], v[104:107], v[0:3], 0
	v_mfma_f32_16x16x32_bf16 v[104:107], v[104:107], v[8:11], 0
	s_waitcnt lgkmcnt(10)
	v_mfma_f32_16x16x32_bf16 v[136:139], v[108:111], v[8:11], 0
	v_mfma_f32_16x16x32_bf16 v[132:135], v[108:111], v[0:3], 0
	s_waitcnt lgkmcnt(9)
	v_mfma_f32_16x16x32_bf16 v[128:131], v[112:115], v[4:7], v[128:131]
	v_mfma_f32_16x16x32_bf16 v[108:111], v[112:115], v[12:15], v[104:107]
	s_waitcnt lgkmcnt(8)
	v_mfma_f32_16x16x32_bf16 v[104:107], v[116:119], v[12:15], v[136:139]
	v_mfma_f32_16x16x32_bf16 v[132:135], v[116:119], v[4:7], v[132:135]
	s_waitcnt lgkmcnt(7)
	s_nop 1
	s_nop 0
	v_fmamk_f32 v127, v128, 0x3e38aa3b, v153
	v_fmamk_f32 v116, v129, 0x3e38aa3b, v152
	s_waitcnt lgkmcnt(6)
	v_fmamk_f32 v117, v130, 0x3e38aa3b, v155
	v_fmamk_f32 v114, v131, 0x3e38aa3b, v154
	s_waitcnt lgkmcnt(5)
	v_fmamk_f32 v113, v132, 0x3e38aa3b, v157
	v_fmamk_f32 v112, v133, 0x3e38aa3b, v156
	v_max3_f32 v115, v127, v116, v117
	s_waitcnt lgkmcnt(4)
	v_fmamk_f32 v128, v134, 0x3e38aa3b, v169
	v_fmamk_f32 v118, v135, 0x3e38aa3b, v168
	v_max3_f32 v119, v114, v113, v112
	v_max_f32_e32 v120, v128, v118
	v_max3_f32 v115, v120, v115, v119
	v_cndmask_b32_e64 v115, v115, v225, s[36:37]
	v_add_f32_e32 v119, 0x41000000, v188
	v_cmp_gt_f32_e32 vcc, v115, v119
	s_cbranch_vccz .LBB0_461
	ds_bpermute_b32 v119, v233, v115
	v_max_f32_e32 v115, v115, v115
	v_mov_b32_e32 v121, v189
	s_waitcnt lgkmcnt(0)
	v_max_f32_e32 v119, v119, v119
	v_max_f32_e32 v115, v115, v119
	ds_bpermute_b32 v119, v234, v115
	s_waitcnt lgkmcnt(0)
	v_max3_f32 v120, v188, v115, v119
	v_sub_f32_e32 v115, v188, v120
	v_exp_f32_e32 v130, v115
	v_mov_b64_e32 v[188:189], v[120:121]
	v_mul_f32_e32 v146, v146, v130
	v_pk_mul_f32 v[30:31], v[30:31], v[130:131] op_sel_hi:[1,0]
	v_pk_mul_f32 v[28:29], v[28:29], v[130:131] op_sel_hi:[1,0]
	v_pk_mul_f32 v[26:27], v[26:27], v[130:131] op_sel_hi:[1,0]
	v_pk_mul_f32 v[24:25], v[24:25], v[130:131] op_sel_hi:[1,0]
	v_pk_mul_f32 v[22:23], v[22:23], v[130:131] op_sel_hi:[1,0]
	v_pk_mul_f32 v[20:21], v[20:21], v[130:131] op_sel_hi:[1,0]
	v_pk_mul_f32 v[18:19], v[18:19], v[130:131] op_sel_hi:[1,0]
	v_pk_mul_f32 v[16:17], v[16:17], v[130:131] op_sel_hi:[1,0]
	s_branch .LBB0_462

; #define TIDX opaque_tid()
; __device__ __forceinline__ unsigned pk2(float lo, float hi) { const f32x2v v = {lo, hi}; const bf16x2v r = __builtin_convertvector(v, bf16x2v); return __builtin_bit_cast(unsigned, r); }
; __device__ __forceinline__ void kv_lwrite(const KVRegs& r, char* lds, int buf) {
;   const int tid = TIDX, row = tid >> 3, cq = tid & 7;
;   char* kt = lds + NSA_KT + buf * 8192 + row * 128;
;   *(u32x4*)(kt + ((cq ^ (row & 7)) << 4)) = r.k0;
;   bf16_t* vt = (bf16_t*)(lds + NSA_VT + buf * 8704) + (cq * 8) * 68 + row;
; #pragma unroll
;   for (int i = 0; i < 4; ++i) { vt[(2 * i) * 68] = (bf16_t)(r.v0[i] & 0xffffu); vt[(2 * i + 1) * 68] = (bf16_t)(r.v0[i] >> 16); }
; }
; template <int MODE>
; __device__ __forceinline__ void nsa_compute(int cur, int buf, int t, int hl, u64 mymask, const bf16x8 (&Qf)[2][2], f32x4 (&O)[4][2], float (&m)[2], float (&l)[2],
;                                             const float (&inv)[2], float* impw, char* lds) {
;     ...
;         const float me = (MODE == 2) ? (selok ? m[r] : __builtin_inff()) : m[r];
;         float ps = 0.f;
; #pragma unroll
;         for (int kk = 0; kk < 2; ++kk)
; #pragma unroll
;           for (int e = 0; e < 4; ++e) { pv[kk][e] = __builtin_amdgcn_exp2f(sv[kk][e] - me); ps += pv[kk][e]; }
;         l[r] += ps;
;       }
;       if (MODE != 0) {
;         const unsigned w0 = pk2(pv[0][0], pv[0][1]), w1 = pk2(pv[0][2], pv[0][3]), w2 = pk2(pv[1][0], pv[1][1]), w3 = pk2(pv[1][2], pv[1][3]);
;         u32x4 pw; pw.x = w0; pw.y = w1; pw.z = w2; pw.w = w3;
;         Pf[r] = __builtin_bit_cast(bf16x8, pw);
;       }
;     }
;     if (MODE != 0) {
;       bf16x8 vfr[4];
; #pragma unroll
;       for (int df = 0; df < 4; ++df) {
;         const bf16x4 va = *(const bf16x4*)(vt + (df * 16 + fr) * 68 + 32 * s2 + 4 * fq);
;         const bf16x4 vb = *(const bf16x4*)(vt + (df * 16 + fr) * 68 + 32 * s2 + 16 + 4 * fq);
;         bf16x8 vf; vf[0] = va[0]; vf[1] = va[1]; vf[2] = va[2]; vf[3] = va[3]; vf[4] = vb[0]; vf[5] = vb[1]; vf[6] = vb[2]; vf[7] = vb[3];
;         vfr[df] = vf;
;       }
;       __builtin_amdgcn_s_setprio(1);
; #pragma unroll
;       for (int df = 0; df < 4; ++df)
; #pragma unroll
;         for (int r = 0; r < 2; ++r) O[df][r] = mfma16(vfr[df], Pf[r], O[df][r]);
;       __builtin_amdgcn_s_setprio(0);
.LBB0_465:
	v_cndmask_b32_e64 v106, v106, v228, s[36:37]
	v_sub_f32_e32 v107, v113, v106
	v_exp_f32_e32 v136, v107
	v_sub_f32_e32 v107, v112, v106
	v_exp_f32_e32 v137, v107
	v_sub_f32_e32 v107, v109, v106
	v_exp_f32_e32 v138, v107
	v_sub_f32_e32 v107, v108, v106
	v_exp_f32_e32 v139, v107
	v_sub_f32_e32 v107, v111, v106
	v_cvt_pk_bf16_f32 v132, v115, v116
	v_cvt_pk_bf16_f32 v133, v117, v114
	v_cvt_pk_bf16_f32 v134, v119, v120
	v_cvt_pk_bf16_f32 v135, v121, v118
	v_exp_f32_e32 v140, v107
	v_sub_f32_e32 v107, v110, v106
	ds_read2_b64 v[108:111], v123 offset0:8 offset1:12
	ds_read2_b64 v[112:115], v124 offset0:24 offset1:28
	ds_read2_b64 v[116:119], v125 offset0:40 offset1:44
	ds_read2_b64 v[120:123], v126 offset0:56 offset1:60
	v_sub_f32_e32 v105, v105, v106
	v_sub_f32_e32 v104, v104, v106
	v_exp_f32_e32 v141, v107
	v_exp_f32_e32 v142, v105
	v_exp_f32_e32 v143, v104
	v_cvt_pk_bf16_f32 v148, v136, v137
	v_cvt_pk_bf16_f32 v149, v138, v139
	v_cvt_pk_bf16_f32 v150, v140, v141
	v_cvt_pk_bf16_f32 v151, v142, v143
	s_waitcnt lgkmcnt(3)
	v_mfma_f32_16x16x32_bf16 v[104:107], v[108:111], v[132:135], v[28:31]
	v_mfma_f32_16x16x32_bf16 v[108:111], v[108:111], v[148:151], v[44:47]
	s_waitcnt lgkmcnt(2)
	v_mfma_f32_16x16x32_bf16 v[124:127], v[112:115], v[132:135], v[24:27]
	v_mfma_f32_16x16x32_bf16 v[112:115], v[112:115], v[148:151], v[40:43]
	s_waitcnt lgkmcnt(1)
	v_mfma_f32_16x16x32_bf16 v[128:131], v[116:119], v[132:135], v[20:23]
	v_mfma_f32_16x16x32_bf16 v[116:119], v[116:119], v[148:151], v[36:39]
	s_waitcnt lgkmcnt(0)
	v_mfma_f32_16x16x32_bf16 v[132:135], v[120:123], v[132:135], v[16:19]
	v_mfma_f32_16x16x32_bf16 v[120:123], v[120:123], v[148:151], v[32:35]
	s_cmp_lt_i32 s62, 0
	s_cbranch_scc1 .LBB0_467
	v_mov_b32 v16, v179
	s_nop 0
	v_ashrrev_i32_e32 v17, 3, v16
	v_xor_b32_e32 v19, v17, v16
	v_lshlrev_b32_e32 v16, 3, v16
	v_lshlrev_b32_e32 v19, 4, v19
	v_and_b32_e32 v16, 56, v16
	v_lshlrev_b32_e32 v18, 7, v17
	v_and_b32_e32 v19, 0x70, v19
	v_mul_u32_u24_e32 v16, 0x88, v16
	v_lshlrev_b32_e32 v17, 1, v17
	v_add3_u32 v18, s63, v18, v19
	v_add3_u32 v16, s71, v16, v17
	s_waitcnt vmcnt(1)
	ds_write_b128 v18, v[64:67]
	s_waitcnt vmcnt(0)
	ds_write_b16 v16, v68 offset:16384
	ds_write_b16_d16_hi v16, v68 offset:16520
	ds_write_b16 v16, v69 offset:16656
	ds_write_b16_d16_hi v16, v69 offset:16792
	ds_write_b16 v16, v70 offset:16928
	ds_write_b16_d16_hi v16, v70 offset:17064
	ds_write_b16 v16, v71 offset:17200
	ds_write_b16_d16_hi v16, v71 offset:17336

; __device__ __forceinline__ f32x4 mfma16(bf16x8 a, bf16x8 b, f32x4 c) { return __builtin_amdgcn_mfma_f32_16x16x32_bf16(a, b, c, 0, 0, 0); }
; template <int MODE>
; __device__ __forceinline__ void nsa_compute(int cur, int buf, int t, int hl, u64 mymask, const bf16x8 (&Qf)[2][2], f32x4 (&O)[4][2], float (&m)[2], float (&l)[2],
;                                             const float (&inv)[2], float* impw, char* lds) {
;     ...
;   const bool selok = (MODE == 2) ? (((mymask >> cur) & 1ull) != 0ull) : true;
;   const float* tb = (MODE == 3) ? (const float*)(lds + NSA_TW) + hl * 640 : (const float*)(lds + NSA_T) + hl * 4160;
;   constexpr int TS = (MODE == 3) ? 640 : 4160;
;   const int base = (MODE <= 1) ? (t - 31 - 16 * (cur * 64 + 4 * fq) + 64) : (t - cur * 64 - 4 * fq + 64);
; #pragma unroll
;   for (int s2 = 0; s2 < 2; ++s2) {
;     f32x4 S[2][2] = {};
;     bf16x8 kfr[2][2];
; #pragma unroll
;     for (int ks = 0; ks < 2; ++ks)
; #pragma unroll
;       for (int kk = 0; kk < 2; ++kk) kfr[ks][kk] = *(const bf16x8*)(kt + (32 * s2 + 16 * kk + fr) * 128 + (((ks * 4 + fq) ^ (fr & 7)) << 4));
;     __builtin_amdgcn_s_setprio(1);
; #pragma unroll
;     for (int ks = 0; ks < 2; ++ks)
; #pragma unroll
;       for (int kk = 0; kk < 2; ++kk)
; #pragma unroll
;         for (int r = 0; r < 2; ++r) S[kk][r] = mfma16(kfr[ks][kk], Qf[r][ks], S[kk][r]);
;     __builtin_amdgcn_s_setprio(0);
;     bf16x8 Pf[2];
;     float g1s[2] = {0.f, 0.f}, p3s[2] = {0.f, 0.f};
; #pragma unroll
;     for (int r = 0; r < 2; ++r) {
;       float sv[2][4];
; #pragma unroll
;       for (int kk = 0; kk < 2; ++kk)
; #pragma unroll
;         for (int e = 0; e < 4; ++e) {
;           const int off = 32 * s2 + 16 * kk + e;
;           int idx;
;           if (MODE <= 1) { idx = base - 16 * off; idx = idx > 0 ? idx : 0; } else idx = base - off;
;           sv[kk][e] = S[kk][r][e] * (0.125f * LOG2E) + tb[r * TS + idx];
;         }
;     ...
;         float ps = 0.f;
; #pragma unroll
;         for (int kk = 0; kk < 2; ++kk)
; #pragma unroll
;           for (int e = 0; e < 4; ++e) { pv[kk][e] = __builtin_amdgcn_exp2f(sv[kk][e] - me); ps += pv[kk][e]; }
;         l[r] += ps;
.LBB0_469:
	v_add_f32_e32 v16, 0, v136
	v_add_f32_e32 v16, v137, v16
	v_add_f32_e32 v16, v138, v16
	v_add_f32_e32 v16, v139, v16
	v_add_f32_e32 v16, v140, v16
	v_add_f32_e32 v16, v141, v16
	v_add_f32_e32 v16, v142, v16
	v_add_f32_e32 v16, v143, v16
	v_add_f32_e32 v147, v147, v16
	s_mov_b64 s[36:37], -1
	s_cmp_lt_i32 s62, 0
	s_mov_b64 vcc, -1
	s_cbranch_scc1 .LBB0_487
	s_lshl_b64 s[36:37], 1, s62
	v_mov_b32 v18, v179
	v_and_b32_e32 v17, s37, v187
	v_lshrrev_b32_e32 v19, 4, v18
	v_bfe_u32 v24, v18, 4, 2
	v_and_b32_e32 v16, s36, v186
	v_and_b32_e32 v25, 7, v18
	v_and_b32_e32 v150, 15, v18
	v_cmp_eq_u64_e64 s[36:37], 0, v[16:17]
	v_lshlrev_b32_e32 v151, 2, v24
	v_bitop3_b32 v16, v19, v25, 3 bitop3:0x6c
	v_bitop3_b32 v24, v24, v25, 4 bitop3:0x36
	v_lshlrev_b32_e32 v26, 7, v150
	v_lshl_add_u32 v16, v16, 4, s63
	v_lshl_add_u32 v24, v24, 4, s63
	v_add_u32_e32 v148, v16, v26
	v_add_u32_e32 v149, v24, v26
	ds_read_b128 v[16:19], v148
	ds_read_b128 v[20:23], v148 offset:2048
	ds_read_b128 v[24:27], v149
	ds_read_b128 v[32:35], v149 offset:2048
	v_sub_u32_e32 v251, v180, v151
	v_lshl_add_u32 v251, v251, 2, v181
	s_lshl_b32 s16, s62, 8
	v_subrev_u32_e32 v250, s16, v251
	v_add_u32_e32 v249, 0x8400, v250
	v_add_u32_e32 v248, 0xc500, v250
	ds_read2_b32 v[192:193], v249 offset0:63 offset1:64
	ds_read2_b32 v[194:195], v249 offset0:61 offset1:62
	ds_read2_b32 v[198:199], v249 offset0:47 offset1:48
	ds_read2_b32 v[200:201], v249 offset0:45 offset1:46
	ds_read2_b32 v[202:203], v248 offset0:63 offset1:64
	ds_read2_b32 v[204:205], v248 offset0:61 offset1:62
	ds_read2_b32 v[206:207], v248 offset0:47 offset1:48
	ds_read2_b32 v[208:209], v248 offset0:45 offset1:46
	s_waitcnt lgkmcnt(11)
	v_mfma_f32_16x16x32_bf16 v[28:31], v[16:19], v[0:3], 0
	v_mfma_f32_16x16x32_bf16 v[16:19], v[16:19], v[8:11], 0
	s_waitcnt lgkmcnt(10)
	v_mfma_f32_16x16x32_bf16 v[36:39], v[20:23], v[0:3], 0
	v_mfma_f32_16x16x32_bf16 v[20:23], v[20:23], v[8:11], 0
	s_waitcnt lgkmcnt(9)
	v_mfma_f32_16x16x32_bf16 v[40:43], v[24:27], v[4:7], v[28:31]
	v_mfma_f32_16x16x32_bf16 v[28:31], v[24:27], v[12:15], v[16:19]
	s_waitcnt lgkmcnt(8)
	v_mfma_f32_16x16x32_bf16 v[16:19], v[32:35], v[4:7], v[36:39]
	v_mfma_f32_16x16x32_bf16 v[20:23], v[32:35], v[12:15], v[20:23]
	v_sub_u32_e32 v24, v180, v151
	v_lshl_add_u32 v24, v24, 2, v181
	v_subrev_u32_e32 v158, s16, v24
	s_waitcnt lgkmcnt(7)
	v_fmamk_f32 v47, v40, 0x3e38aa3b, v193
	v_fmamk_f32 v46, v41, 0x3e38aa3b, v192
	s_waitcnt lgkmcnt(6)
	v_fmamk_f32 v39, v42, 0x3e38aa3b, v195
	v_fmamk_f32 v38, v43, 0x3e38aa3b, v194
	s_waitcnt lgkmcnt(5)
	v_fmamk_f32 v37, v16, 0x3e38aa3b, v199
	v_fmamk_f32 v36, v17, 0x3e38aa3b, v198
	v_max3_f32 v16, v47, v46, v39
	v_max3_f32 v17, v38, v37, v36
	s_waitcnt lgkmcnt(4)
	v_fmamk_f32 v45, v18, 0x3e38aa3b, v201
	v_fmamk_f32 v44, v19, 0x3e38aa3b, v200
	v_max_f32_e32 v18, v45, v44
	v_max3_f32 v16, v18, v16, v17
	v_cndmask_b32_e64 v16, v16, v225, s[36:37]
	v_add_f32_e32 v17, 0x41000000, v188
	v_cmp_gt_f32_e32 vcc, v16, v17
	s_cbranch_vccz .LBB0_472
	ds_bpermute_b32 v17, v233, v16
	v_max_f32_e32 v16, v16, v16
	v_mov_b32_e32 v137, v189
	v_mov_b32_e32 v191, v147
	s_waitcnt lgkmcnt(0)
	v_max_f32_e32 v17, v17, v17
	v_max_f32_e32 v16, v16, v17
	ds_bpermute_b32 v17, v234, v16
	s_waitcnt lgkmcnt(0)
	v_max3_f32 v136, v188, v16, v17
	v_sub_f32_e32 v16, v188, v136
	v_exp_f32_e32 v40, v16
	v_mov_b64_e32 v[188:189], v[136:137]
	v_mul_f32_e32 v190, v146, v40
	v_pk_mul_f32 v[18:19], v[106:107], v[40:41] op_sel_hi:[1,0]
	v_pk_mul_f32 v[16:17], v[104:105], v[40:41] op_sel_hi:[1,0]
	v_pk_mul_f32 v[26:27], v[126:127], v[40:41] op_sel_hi:[1,0]
	v_pk_mul_f32 v[24:25], v[124:125], v[40:41] op_sel_hi:[1,0]
	v_pk_mul_f32 v[34:35], v[130:131], v[40:41] op_sel_hi:[1,0]
	v_pk_mul_f32 v[32:33], v[128:129], v[40:41] op_sel_hi:[1,0]
	v_pk_mul_f32 v[42:43], v[134:135], v[40:41] op_sel_hi:[1,0]
	v_pk_mul_f32 v[40:41], v[132:133], v[40:41] op_sel_hi:[1,0]
	s_branch .LBB0_473

; template <int MODE>
; __device__ __forceinline__ void nsa_compute(int cur, int buf, int t, int hl, u64 mymask, const bf16x8 (&Qf)[2][2], f32x4 (&O)[4][2], float (&m)[2], float (&l)[2],
;                                             const float (&inv)[2], float* impw, char* lds) {
;     ...
;     for (int ks = 0; ks < 2; ++ks)
; #pragma unroll
;       for (int kk = 0; kk < 2; ++kk) kfr[ks][kk] = *(const bf16x8*)(kt + (32 * s2 + 16 * kk + fr) * 128 + (((ks * 4 + fq) ^ (fr & 7)) << 4));
;     __builtin_amdgcn_s_setprio(1);
; #pragma unroll
;     for (int ks = 0; ks < 2; ++ks)
; #pragma unroll
;       for (int kk = 0; kk < 2; ++kk)
; #pragma unroll
;         for (int r = 0; r < 2; ++r) S[kk][r] = mfma16(kfr[ks][kk], Qf[r][ks], S[kk][r]);
;     __builtin_amdgcn_s_setprio(0);
;     bf16x8 Pf[2];
;     float g1s[2] = {0.f, 0.f}, p3s[2] = {0.f, 0.f};
; #pragma unroll
;     for (int r = 0; r < 2; ++r) {
;       float sv[2][4];
; #pragma unroll
;       for (int kk = 0; kk < 2; ++kk)
; #pragma unroll
;         for (int e = 0; e < 4; ++e) {
;           const int off = 32 * s2 + 16 * kk + e;
;           int idx;
;           if (MODE <= 1) { idx = base - 16 * off; idx = idx > 0 ? idx : 0; } else idx = base - off;
;     ...
;           for (int e = 0; e < 4; ++e) { pv[kk][e] = __builtin_amdgcn_exp2f(sv[kk][e] - me); ps += pv[kk][e]; }
;         l[r] += ps;
;       }
;       if (MODE != 0) {
;         const unsigned w0 = pk2(pv[0][0], pv[0][1]), w1 = pk2(pv[0][2], pv[0][3]), w2 = pk2(pv[1][0], pv[1][1]), w3 = pk2(pv[1][2], pv[1][3]);
;         u32x4 pw; pw.x = w0; pw.y = w1; pw.z = w2; pw.w = w3;
;         Pf[r] = __builtin_bit_cast(bf16x8, pw);
;       }
;     }
;     if (MODE != 0) {
;       bf16x8 vfr[4];
; #pragma unroll
;       for (int df = 0; df < 4; ++df) {
;         const bf16x4 va = *(const bf16x4*)(vt + (df * 16 + fr) * 68 + 32 * s2 + 4 * fq);
;         const bf16x4 vb = *(const bf16x4*)(vt + (df * 16 + fr) * 68 + 32 * s2 + 16 + 4 * fq);
;         bf16x8 vf; vf[0] = va[0]; vf[1] = va[1]; vf[2] = va[2]; vf[3] = va[3]; vf[4] = vb[0]; vf[5] = vb[1]; vf[6] = vb[2]; vf[7] = vb[3];
;         vfr[df] = vf;
;       }
;       __builtin_amdgcn_s_setprio(1);
; #pragma unroll
;       for (int df = 0; df < 4; ++df)
; #pragma unroll
;         for (int r = 0; r < 2; ++r) O[df][r] = mfma16(vfr[df], Pf[r], O[df][r]);
;       __builtin_amdgcn_s_setprio(0);
.LBB0_476:
	v_cvt_pk_bf16_f32 v152, v152, v153
	v_cvt_pk_bf16_f32 v153, v154, v155
	v_cvt_pk_bf16_f32 v154, v156, v157
	v_cndmask_b32_e64 v156, v161, v228, s[36:37]
	v_sub_f32_e32 v139, v139, v156
	v_exp_f32_e32 v139, v139
	v_sub_f32_e32 v138, v138, v156
	v_exp_f32_e32 v138, v138
	v_sub_f32_e32 v141, v141, v156
	v_exp_f32_e32 v141, v141
	v_sub_f32_e32 v140, v140, v156
	v_exp_f32_e32 v140, v140
	v_sub_f32_e32 v137, v137, v156
	v_cvt_pk_bf16_f32 v155, v159, v160
	v_add_f32_e32 v157, 0, v139
	v_exp_f32_e32 v159, v137
	v_add_f32_e32 v157, v138, v157
	v_add_f32_e32 v157, v141, v157
	v_add_f32_e32 v157, v140, v157
	v_sub_f32_e32 v136, v136, v156
	v_add_f32_e32 v137, v159, v157
	v_exp_f32_e32 v157, v136
	s_nop 0
	v_add_f32_e32 v136, v157, v137
	v_sub_f32_e32 v137, v143, v156
	v_exp_f32_e32 v143, v137
	v_sub_f32_e32 v137, v142, v156
	v_exp_f32_e32 v142, v137
	v_cvt_pk_bf16_f32 v137, v141, v140
	v_mul_u32_u24_e32 v140, 0x44, v150
	v_add_f32_e32 v136, v143, v136
	v_lshlrev_b32_e32 v140, 1, v140
	v_lshlrev_b32_e32 v141, 1, v151
	v_add_f32_e32 v136, v142, v136
	v_add3_u32 v150, s71, v140, v141
	v_add_f32_e32 v191, v191, v136
	v_cvt_pk_bf16_f32 v136, v139, v138
	v_cvt_pk_bf16_f32 v138, v159, v157
	v_add_u32_e32 v159, 0x4000, v150
	v_add_u32_e32 v160, 0x4800, v150
	v_cvt_pk_bf16_f32 v139, v143, v142
	ds_read2_b64 v[140:143], v159 offset1:4
	ds_read2_b64 v[164:167], v160 offset0:16 offset1:20
	v_add_u32_e32 v161, 0x5000, v150
	v_add_u32_e32 v162, 0x5800, v150
	ds_read2_b64 v[168:171], v161 offset0:32 offset1:36
	ds_read2_b64 v[172:175], v162 offset0:48 offset1:52
	s_waitcnt lgkmcnt(3)
	v_mfma_f32_16x16x32_bf16 v[16:19], v[140:143], v[152:155], v[16:19]
	v_mfma_f32_16x16x32_bf16 v[20:23], v[140:143], v[136:139], v[20:23]
	s_waitcnt lgkmcnt(2)
	v_mfma_f32_16x16x32_bf16 v[24:27], v[164:167], v[152:155], v[24:27]
	v_mfma_f32_16x16x32_bf16 v[28:31], v[164:167], v[136:139], v[28:31]
	s_waitcnt lgkmcnt(1)
	v_mfma_f32_16x16x32_bf16 v[32:35], v[168:171], v[152:155], v[32:35]
	v_mfma_f32_16x16x32_bf16 v[36:39], v[168:171], v[136:139], v[36:39]
	s_waitcnt lgkmcnt(0)
	v_mfma_f32_16x16x32_bf16 v[40:43], v[172:175], v[152:155], v[40:43]
	v_mfma_f32_16x16x32_bf16 v[44:47], v[172:175], v[136:139], v[44:47]
	ds_read_b128 v[136:139], v148 offset:4096
	ds_read_b128 v[140:143], v148 offset:6144
	ds_read_b128 v[150:153], v149 offset:4096
	ds_read_b128 v[154:157], v149 offset:6144
	v_add_u32_e32 v251, 0x8400, v158
	v_add_u32_e32 v250, 0xc500, v158
	ds_read2_b32 v[192:193], v251 offset0:31 offset1:32
	ds_read2_b32 v[194:195], v251 offset0:29 offset1:30
	ds_read2_b32 v[198:199], v251 offset0:15 offset1:16
	ds_read2_b32 v[200:201], v251 offset0:13 offset1:14
	ds_read2_b32 v[202:203], v250 offset0:31 offset1:32
	ds_read2_b32 v[204:205], v250 offset0:29 offset1:30
	ds_read2_b32 v[206:207], v250 offset0:15 offset1:16
	ds_read2_b32 v[208:209], v250 offset0:13 offset1:14
	s_waitcnt lgkmcnt(11)
	v_mfma_f32_16x16x32_bf16 v[164:167], v[136:139], v[0:3], 0
	v_mfma_f32_16x16x32_bf16 v[136:139], v[136:139], v[8:11], 0
	s_waitcnt lgkmcnt(10)
	v_mfma_f32_16x16x32_bf16 v[172:175], v[140:143], v[8:11], 0
	v_mfma_f32_16x16x32_bf16 v[168:171], v[140:143], v[0:3], 0
	s_waitcnt lgkmcnt(9)
	v_mfma_f32_16x16x32_bf16 v[164:167], v[150:153], v[4:7], v[164:167]
	v_mfma_f32_16x16x32_bf16 v[140:143], v[150:153], v[12:15], v[136:139]
	s_waitcnt lgkmcnt(8)
	v_mfma_f32_16x16x32_bf16 v[136:139], v[154:157], v[12:15], v[172:175]
	v_mfma_f32_16x16x32_bf16 v[168:171], v[154:157], v[4:7], v[168:171]
	s_waitcnt lgkmcnt(7)
	s_nop 1
	s_nop 0
	v_fmamk_f32 v163, v164, 0x3e38aa3b, v193
	v_fmamk_f32 v152, v165, 0x3e38aa3b, v192
	s_waitcnt lgkmcnt(6)
	v_fmamk_f32 v153, v166, 0x3e38aa3b, v195
	v_fmamk_f32 v150, v167, 0x3e38aa3b, v194
	s_waitcnt lgkmcnt(5)
	v_fmamk_f32 v149, v168, 0x3e38aa3b, v199
	v_fmamk_f32 v148, v169, 0x3e38aa3b, v198
	v_max3_f32 v151, v163, v152, v153
	s_waitcnt lgkmcnt(4)
	v_fmamk_f32 v164, v170, 0x3e38aa3b, v201
	v_fmamk_f32 v154, v171, 0x3e38aa3b, v200
	v_max3_f32 v155, v150, v149, v148
	v_max_f32_e32 v156, v164, v154
	v_max3_f32 v151, v156, v151, v155
	v_cndmask_b32_e64 v151, v151, v225, s[36:37]
	v_add_f32_e32 v155, 0x41000000, v188
	v_cmp_gt_f32_e32 vcc, v151, v155
	s_cbranch_vccz .LBB0_478
	ds_bpermute_b32 v155, v233, v151
	v_max_f32_e32 v151, v151, v151
	v_mov_b32_e32 v157, v189
	s_waitcnt lgkmcnt(0)
	v_max_f32_e32 v155, v155, v155
	v_max_f32_e32 v151, v151, v155
	ds_bpermute_b32 v155, v234, v151
	s_waitcnt lgkmcnt(0)
	v_max3_f32 v156, v188, v151, v155
	v_sub_f32_e32 v151, v188, v156
	v_exp_f32_e32 v166, v151
	v_mov_b64_e32 v[188:189], v[156:157]
	v_mul_f32_e32 v190, v190, v166
	v_pk_mul_f32 v[18:19], v[18:19], v[166:167] op_sel_hi:[1,0]
	v_pk_mul_f32 v[16:17], v[16:17], v[166:167] op_sel_hi:[1,0]
	v_pk_mul_f32 v[26:27], v[26:27], v[166:167] op_sel_hi:[1,0]
	v_pk_mul_f32 v[24:25], v[24:25], v[166:167] op_sel_hi:[1,0]
	v_pk_mul_f32 v[34:35], v[34:35], v[166:167] op_sel_hi:[1,0]
	v_pk_mul_f32 v[32:33], v[32:33], v[166:167] op_sel_hi:[1,0]
	v_pk_mul_f32 v[42:43], v[42:43], v[166:167] op_sel_hi:[1,0]
	v_pk_mul_f32 v[40:41], v[40:41], v[166:167] op_sel_hi:[1,0]
	s_branch .LBB0_479

; #define TIDX opaque_tid()
; __device__ __forceinline__ unsigned pk2(float lo, float hi) { const f32x2v v = {lo, hi}; const bf16x2v r = __builtin_convertvector(v, bf16x2v); return __builtin_bit_cast(unsigned, r); }
; __device__ __forceinline__ void kv_lwrite(const KVRegs& r, char* lds, int buf) {
;   const int tid = TIDX, row = tid >> 3, cq = tid & 7;
;   char* kt = lds + NSA_KT + buf * 8192 + row * 128;
;   *(u32x4*)(kt + ((cq ^ (row & 7)) << 4)) = r.k0;
;   bf16_t* vt = (bf16_t*)(lds + NSA_VT + buf * 8704) + (cq * 8) * 68 + row;
; #pragma unroll
;   for (int i = 0; i < 4; ++i) { vt[(2 * i) * 68] = (bf16_t)(r.v0[i] & 0xffffu); vt[(2 * i + 1) * 68] = (bf16_t)(r.v0[i] >> 16); }
; }
; template <int MODE>
; __device__ __forceinline__ void nsa_compute(int cur, int buf, int t, int hl, u64 mymask, const bf16x8 (&Qf)[2][2], f32x4 (&O)[4][2], float (&m)[2], float (&l)[2],
;                                             const float (&inv)[2], float* impw, char* lds) {
;     ...
;         const float me = (MODE == 2) ? (selok ? m[r] : __builtin_inff()) : m[r];
;         float ps = 0.f;
; #pragma unroll
;         for (int kk = 0; kk < 2; ++kk)
; #pragma unroll
;           for (int e = 0; e < 4; ++e) { pv[kk][e] = __builtin_amdgcn_exp2f(sv[kk][e] - me); ps += pv[kk][e]; }
;         l[r] += ps;
;       }
;       if (MODE != 0) {
;         const unsigned w0 = pk2(pv[0][0], pv[0][1]), w1 = pk2(pv[0][2], pv[0][3]), w2 = pk2(pv[1][0], pv[1][1]), w3 = pk2(pv[1][2], pv[1][3]);
;         u32x4 pw; pw.x = w0; pw.y = w1; pw.z = w2; pw.w = w3;
;         Pf[r] = __builtin_bit_cast(bf16x8, pw);
;       }
;     }
;     if (MODE != 0) {
;       bf16x8 vfr[4];
; #pragma unroll
;       for (int df = 0; df < 4; ++df) {
;         const bf16x4 va = *(const bf16x4*)(vt + (df * 16 + fr) * 68 + 32 * s2 + 4 * fq);
;         const bf16x4 vb = *(const bf16x4*)(vt + (df * 16 + fr) * 68 + 32 * s2 + 16 + 4 * fq);
;         bf16x8 vf; vf[0] = va[0]; vf[1] = va[1]; vf[2] = va[2]; vf[3] = va[3]; vf[4] = vb[0]; vf[5] = vb[1]; vf[6] = vb[2]; vf[7] = vb[3];
;         vfr[df] = vf;
;       }
;       __builtin_amdgcn_s_setprio(1);
; #pragma unroll
;       for (int df = 0; df < 4; ++df)
; #pragma unroll
;         for (int r = 0; r < 2; ++r) O[df][r] = mfma16(vfr[df], Pf[r], O[df][r]);
;       __builtin_amdgcn_s_setprio(0);
.LBB0_482:
	v_cndmask_b32_e64 v163, v137, v228, s[36:37]
	v_cvt_pk_bf16_f32 v164, v151, v152
	v_cvt_pk_bf16_f32 v165, v153, v150
	v_cvt_pk_bf16_f32 v166, v155, v156
	v_cvt_pk_bf16_f32 v167, v157, v154
	v_sub_f32_e32 v137, v149, v163
	v_sub_f32_e32 v138, v148, v163
	v_sub_f32_e32 v139, v141, v163
	v_sub_f32_e32 v140, v140, v163
	v_sub_f32_e32 v141, v143, v163
	v_sub_f32_e32 v142, v142, v163
	v_sub_f32_e32 v143, v158, v163
	v_sub_f32_e32 v136, v136, v163
	ds_read2_b64 v[148:151], v159 offset0:8 offset1:12
	ds_read2_b64 v[152:155], v160 offset0:24 offset1:28
	ds_read2_b64 v[156:159], v161 offset0:40 offset1:44
	ds_read2_b64 v[160:163], v162 offset0:56 offset1:60
	v_exp_f32_e32 v137, v137
	v_exp_f32_e32 v138, v138
	v_exp_f32_e32 v139, v139
	v_exp_f32_e32 v140, v140
	v_exp_f32_e32 v141, v141
	v_exp_f32_e32 v142, v142
	v_exp_f32_e32 v143, v143
	v_exp_f32_e32 v136, v136
	v_cvt_pk_bf16_f32 v168, v137, v138
	v_cvt_pk_bf16_f32 v169, v139, v140
	v_cvt_pk_bf16_f32 v170, v141, v142
	v_cvt_pk_bf16_f32 v171, v143, v136
	s_waitcnt lgkmcnt(3)
	v_mfma_f32_16x16x32_bf16 v[16:19], v[148:151], v[164:167], v[16:19]
	v_mfma_f32_16x16x32_bf16 v[20:23], v[148:151], v[168:171], v[20:23]
	s_waitcnt lgkmcnt(2)
	v_mfma_f32_16x16x32_bf16 v[24:27], v[152:155], v[164:167], v[24:27]
	v_mfma_f32_16x16x32_bf16 v[28:31], v[152:155], v[168:171], v[28:31]
	s_waitcnt lgkmcnt(1)
	v_mfma_f32_16x16x32_bf16 v[32:35], v[156:159], v[164:167], v[32:35]
	v_mfma_f32_16x16x32_bf16 v[36:39], v[156:159], v[168:171], v[36:39]
	s_waitcnt lgkmcnt(0)
	v_mfma_f32_16x16x32_bf16 v[40:43], v[160:163], v[164:167], v[40:43]
	v_mfma_f32_16x16x32_bf16 v[44:47], v[160:163], v[168:171], v[44:47]
	s_cmp_lt_i32 s75, 0
	s_cbranch_scc1 .LBB0_484
	v_mov_b32 v148, v179
	s_nop 0
	v_ashrrev_i32_e32 v149, 3, v148
	v_xor_b32_e32 v151, v149, v148
	v_lshlrev_b32_e32 v148, 3, v148
	v_lshlrev_b32_e32 v151, 4, v151
	v_and_b32_e32 v148, 56, v148
	v_lshlrev_b32_e32 v150, 7, v149
	v_and_b32_e32 v151, 0x70, v151
	v_mul_u32_u24_e32 v148, 0x88, v148
	v_lshlrev_b32_e32 v149, 1, v149
	v_add3_u32 v150, s72, v150, v151
	v_add3_u32 v148, s73, v148, v149
	s_waitcnt vmcnt(1)
	ds_write_b128 v150, v[48:51]
	s_waitcnt vmcnt(0)
	ds_write_b16 v148, v52 offset:16384
	ds_write_b16_d16_hi v148, v52 offset:16520
	ds_write_b16 v148, v53 offset:16656
	ds_write_b16_d16_hi v148, v53 offset:16792
	ds_write_b16 v148, v54 offset:16928
	ds_write_b16_d16_hi v148, v54 offset:17064
	ds_write_b16 v148, v55 offset:17200
	ds_write_b16_d16_hi v148, v55 offset:17336
